# PW2: phase 1: waves 4-7 convert 3 stages then run their own half of the weight-product compute; waves 0-3 fill both halves, compute theirs, then convert the last stage
# baseline (speedup 1.0000x reference)
; #define LAS __attribute__((address_space(3)))
; __device__ void p_weights_prod(const Args& a, LAS unsigned char* lds) {
;     ...
;         for (int c0 = 0; c0 < 128; c0 += 4) {
;             f32x4 w4[4], m4[4];
; #pragma unroll
;             for (int r2 = 0; r2 < 4; ++r2) w4[r2] = *(const LAS f32x4*)(wt + (4 * rq + r2) * 128 + c0);
; #pragma unroll
;             for (int cc = 0; cc < 4; ++cc) m4[cc] = *(const LAS f32x4*)(mmt + (c0 + cc) * 256 + lc0);
; #pragma unroll
;             for (int r2 = 0; r2 < 4; ++r2)
; #pragma unroll
;                 for (int cc = 0; cc < 4; ++cc) acc[r2] += m4[cc] * w4[r2][cc];
;         }
.Lpw_ka:
	ds_read_b128 v[40:43], v38
	ds_read_b128 v[44:47], v38 offset:1024
	ds_read_b128 v[48:51], v38 offset:2048
	ds_read_b128 v[52:55], v38 offset:3072
	ds_read_b128 v[56:59], v37
	ds_read_b128 v[60:63], v37 offset:16
	ds_read_b128 v[64:67], v37 offset:512
	ds_read_b128 v[68:71], v37 offset:528
	ds_read_b128 v[72:75], v37 offset:1024
	ds_read_b128 v[76:79], v37 offset:1040
	ds_read_b128 v[80:83], v37 offset:1536
	ds_read_b128 v[84:87], v37 offset:1552
	ds_read_b128 v[88:91], v38 offset:4096
	ds_read_b128 v[92:95], v38 offset:5120
	ds_read_b128 v[96:99], v38 offset:6144
	ds_read_b128 v[100:103], v38 offset:7168
	s_waitcnt lgkmcnt(11)
	v_pk_fma_f32 v[8:9], v[56:57], v[42:43], v[8:9] op_sel_hi:[0,1,1]
	v_pk_fma_f32 v[10:11], v[56:57], v[40:41], v[10:11] op_sel_hi:[0,1,1]
	s_waitcnt lgkmcnt(9)
	v_pk_fma_f32 v[20:21], v[64:65], v[42:43], v[20:21] op_sel_hi:[0,1,1]
	v_pk_fma_f32 v[22:23], v[64:65], v[40:41], v[22:23] op_sel_hi:[0,1,1]
	s_waitcnt lgkmcnt(7)
	v_pk_fma_f32 v[12:13], v[72:73], v[42:43], v[12:13] op_sel_hi:[0,1,1]
	v_pk_fma_f32 v[14:15], v[72:73], v[40:41], v[14:15] op_sel_hi:[0,1,1]
	s_waitcnt lgkmcnt(5)
	v_pk_fma_f32 v[16:17], v[42:43], v[80:81], v[16:17] op_sel_hi:[1,0,1]
	v_pk_fma_f32 v[18:19], v[40:41], v[80:81], v[18:19] op_sel_hi:[1,0,1]
	v_pk_fma_f32 v[8:9], v[56:57], v[46:47], v[8:9] op_sel:[1,0,0]
	v_pk_fma_f32 v[10:11], v[56:57], v[44:45], v[10:11] op_sel:[1,0,0]
	v_pk_fma_f32 v[20:21], v[64:65], v[46:47], v[20:21] op_sel:[1,0,0]
	v_pk_fma_f32 v[22:23], v[64:65], v[44:45], v[22:23] op_sel:[1,0,0]
	v_pk_fma_f32 v[12:13], v[72:73], v[46:47], v[12:13] op_sel:[1,0,0]
	v_pk_fma_f32 v[14:15], v[72:73], v[44:45], v[14:15] op_sel:[1,0,0]
	v_pk_fma_f32 v[16:17], v[80:81], v[46:47], v[16:17] op_sel:[1,0,0]
	v_pk_fma_f32 v[18:19], v[80:81], v[44:45], v[18:19] op_sel:[1,0,0]
	v_mov_b32_e32 v40, v59
	v_mov_b32_e32 v42, v67
	v_mov_b32_e32 v104, v75
	v_mov_b32_e32 v106, v83
	v_pk_fma_f32 v[10:11], v[58:59], v[48:49], v[10:11] op_sel_hi:[0,1,1]
	v_pk_fma_f32 v[8:9], v[58:59], v[50:51], v[8:9] op_sel_hi:[0,1,1]
	v_pk_fma_f32 v[22:23], v[66:67], v[48:49], v[22:23] op_sel_hi:[0,1,1]
	v_pk_fma_f32 v[20:21], v[66:67], v[50:51], v[20:21] op_sel_hi:[0,1,1]
	v_pk_fma_f32 v[14:15], v[74:75], v[48:49], v[14:15] op_sel_hi:[0,1,1]
	v_pk_fma_f32 v[12:13], v[74:75], v[50:51], v[12:13] op_sel_hi:[0,1,1]
	v_pk_fma_f32 v[18:19], v[82:83], v[48:49], v[18:19] op_sel_hi:[0,1,1]
	v_pk_fma_f32 v[16:17], v[82:83], v[50:51], v[16:17] op_sel_hi:[0,1,1]
	v_pk_fma_f32 v[8:9], v[40:41], v[54:55], v[8:9] op_sel_hi:[0,1,1]
	v_pk_fma_f32 v[10:11], v[40:41], v[52:53], v[10:11] op_sel_hi:[0,1,1]
	v_pk_fma_f32 v[20:21], v[42:43], v[54:55], v[20:21] op_sel_hi:[0,1,1]
	v_pk_fma_f32 v[22:23], v[42:43], v[52:53], v[22:23] op_sel_hi:[0,1,1]
	v_pk_fma_f32 v[12:13], v[104:105], v[54:55], v[12:13] op_sel_hi:[0,1,1]
	v_pk_fma_f32 v[14:15], v[104:105], v[52:53], v[14:15] op_sel_hi:[0,1,1]
	v_pk_fma_f32 v[16:17], v[106:107], v[54:55], v[16:17] op_sel_hi:[0,1,1]
	v_pk_fma_f32 v[18:19], v[106:107], v[52:53], v[18:19] op_sel_hi:[0,1,1]
	s_waitcnt lgkmcnt(3)
	v_pk_fma_f32 v[10:11], v[60:61], v[88:89], v[10:11] op_sel_hi:[0,1,1]
	v_pk_fma_f32 v[8:9], v[60:61], v[90:91], v[8:9] op_sel_hi:[0,1,1]
	v_pk_fma_f32 v[22:23], v[68:69], v[88:89], v[22:23] op_sel_hi:[0,1,1]
	v_pk_fma_f32 v[20:21], v[68:69], v[90:91], v[20:21] op_sel_hi:[0,1,1]
	v_pk_fma_f32 v[14:15], v[76:77], v[88:89], v[14:15] op_sel_hi:[0,1,1]
	v_pk_fma_f32 v[12:13], v[76:77], v[90:91], v[12:13] op_sel_hi:[0,1,1]
	v_pk_fma_f32 v[18:19], v[88:89], v[84:85], v[18:19] op_sel_hi:[1,0,1]
	v_pk_fma_f32 v[16:17], v[90:91], v[84:85], v[16:17] op_sel_hi:[1,0,1]
	s_waitcnt lgkmcnt(2)
	v_pk_fma_f32 v[8:9], v[60:61], v[94:95], v[8:9] op_sel:[1,0,0]
	v_pk_fma_f32 v[10:11], v[60:61], v[92:93], v[10:11] op_sel:[1,0,0]
	v_pk_fma_f32 v[20:21], v[68:69], v[94:95], v[20:21] op_sel:[1,0,0]
	v_pk_fma_f32 v[22:23], v[68:69], v[92:93], v[22:23] op_sel:[1,0,0]
	v_pk_fma_f32 v[12:13], v[76:77], v[94:95], v[12:13] op_sel:[1,0,0]
	v_pk_fma_f32 v[14:15], v[76:77], v[92:93], v[14:15] op_sel:[1,0,0]
	v_pk_fma_f32 v[16:17], v[84:85], v[94:95], v[16:17] op_sel:[1,0,0]
	v_pk_fma_f32 v[18:19], v[84:85], v[92:93], v[18:19] op_sel:[1,0,0]
	s_add_i32 s10, s10, 8
	v_mov_b32_e32 v108, v63
	v_mov_b32_e32 v110, v71
	v_mov_b32_e32 v112, v79
	v_mov_b32_e32 v114, v87
	s_waitcnt lgkmcnt(1)
	v_pk_fma_f32 v[10:11], v[62:63], v[96:97], v[10:11] op_sel_hi:[0,1,1]
	v_pk_fma_f32 v[8:9], v[62:63], v[98:99], v[8:9] op_sel_hi:[0,1,1]
	v_pk_fma_f32 v[22:23], v[70:71], v[96:97], v[22:23] op_sel_hi:[0,1,1]
	v_pk_fma_f32 v[20:21], v[70:71], v[98:99], v[20:21] op_sel_hi:[0,1,1]
	v_pk_fma_f32 v[14:15], v[78:79], v[96:97], v[14:15] op_sel_hi:[0,1,1]
	v_pk_fma_f32 v[12:13], v[78:79], v[98:99], v[12:13] op_sel_hi:[0,1,1]
	v_pk_fma_f32 v[18:19], v[86:87], v[96:97], v[18:19] op_sel_hi:[0,1,1]
	v_pk_fma_f32 v[16:17], v[86:87], v[98:99], v[16:17] op_sel_hi:[0,1,1]
	v_add_u32_e32 v38, 0x2000, v38
	v_add_u32_e32 v37, 32, v37
	s_cmpk_gt_u32 s10, 0x7b
	s_waitcnt lgkmcnt(0)
	v_pk_fma_f32 v[8:9], v[108:109], v[102:103], v[8:9] op_sel_hi:[0,1,1]
	v_pk_fma_f32 v[10:11], v[108:109], v[100:101], v[10:11] op_sel_hi:[0,1,1]
	v_pk_fma_f32 v[20:21], v[110:111], v[102:103], v[20:21] op_sel_hi:[0,1,1]
	v_pk_fma_f32 v[22:23], v[110:111], v[100:101], v[22:23] op_sel_hi:[0,1,1]
	v_pk_fma_f32 v[12:13], v[112:113], v[102:103], v[12:13] op_sel_hi:[0,1,1]
	v_pk_fma_f32 v[14:15], v[112:113], v[100:101], v[14:15] op_sel_hi:[0,1,1]
	v_pk_fma_f32 v[16:17], v[114:115], v[102:103], v[16:17] op_sel_hi:[0,1,1]
	v_pk_fma_f32 v[18:19], v[114:115], v[100:101], v[18:19] op_sel_hi:[0,1,1]
	s_cbranch_scc0 .Lpw_ka
; __device__ void p0_xconv(const Args& a) {
;     f16* XH = (f16*)(a.ws + WS_XH); float* SS = (float*)(a.ws + WS_SS);
;     int tid_ = threadIdx.x; asm volatile("" : "+v"(tid_));
;     const int lane = tid_ & 63, wv = tid_ >> 6;
;     const int nwv = (int)gridDim.x * 8;
;     for (int row0 = (int)blockIdx.x * 8 + wv; row0 < MROWS; row0 += 4 * nwv) {
;         f32x4 v[4][4];
; #pragma unroll
;         for (int r = 0; r < 4; ++r) {
;             const int row = row0 + r * nwv;
;             if (row < MROWS) {
;                 const float* src = (row < ROWS_PROMPT) ? a.x_prompt + (size_t)row * DM : a.x_sample + (size_t)(row - ROWS_PROMPT) * DM;
; #pragma unroll
;                 for (int i = 0; i < 4; ++i) v[r][i] = __builtin_nontemporal_load((const f32x4*)(src + i * 256 + lane * 4));
; __device__ void p_weights_prod(const Args& a, LAS unsigned char* lds) {
;     ...
;         const int k0 = kblk * 32 + 4 * rq;
;         const f32x4 gn = *(const f32x4*)(a.norm_gain + l * DM + k0);
; #pragma unroll
;         for (int j = 0; j < 4; ++j) {
;             f16x4 o;
; #pragma unroll
;             for (int r2 = 0; r2 < 4; ++r2) o[r2] = (f16)(acc[r2][j] * gn[r2]);
;             *(f16x4*)(W1T + ((size_t)l * N1 + pn * 256 + rho0 + j) * 1024 + k0) = o;
;         }
	v_add_u32_e32 v42, s56, v27
	s_lshl_b32 s56, s55, 10
	s_ashr_i32 s57, s56, 31
	s_lshl_b64 s[56:57], s[56:57], 2
	s_add_u32 s56, s20, s56
	s_addc_u32 s57, s21, s57
	v_ashrrev_i32_e32 v43, 31, v42
	v_lshl_add_u64 v[38:39], v[42:43], 2, s[56:57]
	global_load_dwordx4 v[38:41], v[38:39], off
	s_lshl_b32 s54, s54, 8
	s_mul_hi_i32 s10, s55, 0xb00
	s_mulk_i32 s55, 0xb00
	s_addk_i32 s54, 0x700
	s_add_u32 s54, s55, s54
	s_addc_u32 s10, s10, 0
	v_mov_b32_e32 v44, v22
	v_mov_b32_e32 v45, v14
	v_mov_b32_e32 v14, v23
	v_mov_b32_e32 v22, v20
	v_mov_b32_e32 v23, v12
	v_mov_b32_e32 v12, v21
	v_lshl_add_u64 v[20:21], v[42:43], 1, s[6:7]
	v_or_b32_e32 v42, s54, v2
	v_mov_b32_e32 v43, s10
	v_lshlrev_b64 v[42:43], 11, v[42:43]
	v_lshl_add_u64 v[46:47], v[20:21], 0, v[42:43]
	v_or_b32_e32 v48, 0x800, v42
	v_mov_b32_e32 v49, v43
	v_or_b32_e32 v50, 0x1000, v42
	v_mov_b32_e32 v51, v43
	v_or_b32_e32 v42, 0x1800, v42
	v_lshl_add_u64 v[48:49], v[20:21], 0, v[48:49]
	v_lshl_add_u64 v[50:51], v[20:21], 0, v[50:51]
	v_lshl_add_u64 v[20:21], v[20:21], 0, v[42:43]
	s_add_i32 s53, s53, s9
	s_cmpk_gt_i32 s53, 0xff
	s_waitcnt vmcnt(0)
	v_mov_b32_e32 v42, v39
	v_mov_b32_e32 v43, v40
	v_fma_mixlo_f16 v37, v10, v38, 0
	v_fma_mixlo_f16 v39, v11, v38, 0
	v_fma_mixlo_f16 v40, v8, v38, 0
	v_fma_mixlo_f16 v38, v9, v38, 0
	v_pk_mul_f32 v[8:9], v[44:45], v[42:43]
	v_fma_mixlo_f16 v18, v18, v41, 0
	v_pk_mul_f32 v[10:11], v[14:15], v[42:43]
	v_pk_mul_f32 v[14:15], v[22:23], v[42:43]
	v_pk_mul_f32 v[12:13], v[12:13], v[42:43]
	v_cvt_pk_f16_f32 v9, v8, v9
	v_fma_mixlo_f16 v19, v19, v41, 0
	v_fma_mixlo_f16 v16, v16, v41, 0
	v_fma_mixlo_f16 v17, v17, v41, 0
	v_cvt_pk_f16_f32 v11, v10, v11
	v_cvt_pk_f16_f32 v14, v14, v15
	v_cvt_pk_f16_f32 v15, v12, v13
	v_pack_b32_f16 v8, v37, v9
	v_alignbit_b32 v9, v18, v9, 16
	v_pack_b32_f16 v10, v39, v11
	v_alignbit_b32 v11, v19, v11, 16
	v_pack_b32_f16 v12, v40, v14
	v_alignbit_b32 v13, v16, v14, 16
	v_pack_b32_f16 v14, v38, v15
	v_alignbit_b32 v15, v17, v15, 16
	global_store_dwordx2 v[46:47], v[8:9], off
	global_store_dwordx2 v[48:49], v[10:11], off
	global_store_dwordx2 v[50:51], v[12:13], off
	global_store_dwordx2 v[20:21], v[14:15], off
	v_and_b32_e32 v136, 63, v0
	v_lshrrev_b32_e32 v137, 6, v0
	s_nop 0
	v_readfirstlane_b32 s3, v137
	s_nop 3
	s_lshl_b32 s4, s2, 2
	s_add_i32 s3, s3, s4
	s_mov_b64 s[12:13], 1
	v_xor_b32_e32 v130, 1, v136
	v_lshlrev_b32_e32 v130, 2, v130
	v_xor_b32_e32 v131, 2, v136
	v_lshlrev_b32_e32 v131, 2, v131
	v_xor_b32_e32 v132, 4, v136
	v_lshlrev_b32_e32 v132, 2, v132
	v_xor_b32_e32 v133, 8, v136
	v_lshlrev_b32_e32 v133, 2, v133
	v_xor_b32_e32 v134, 16, v136
	v_lshlrev_b32_e32 v134, 2, v134
	v_xor_b32_e32 v135, 32, v136
	v_lshlrev_b32_e32 v135, 2, v135
	v_lshlrev_b32_e32 v140, 4, v136
	v_lshlrev_b32_e32 v144, 3, v136
	v_lshlrev_b32_e32 v186, 2, v136
	v_lshlrev_b32_e32 v141, 4, v136
	v_add_u32_e32 v141, 0x400000, v141
	v_lshlrev_b32_e32 v145, 3, v136
	v_add_u32_e32 v145, 0x200000, v145
	v_lshlrev_b32_e32 v187, 2, v136
	v_add_u32_e32 v187, 0x10000, v187
	v_lshlrev_b32_e32 v142, 4, v136
	v_add_u32_e32 v142, 0x800000, v142
	v_lshlrev_b32_e32 v146, 3, v136
	v_add_u32_e32 v146, 0x400000, v146
	v_lshlrev_b32_e32 v188, 2, v136
	v_add_u32_e32 v188, 0x20000, v188
	v_lshlrev_b32_e32 v143, 4, v136
	v_add_u32_e32 v143, 0xc00000, v143
	v_lshlrev_b32_e32 v147, 3, v136
	v_add_u32_e32 v147, 0x600000, v147
	v_lshlrev_b32_e32 v189, 2, v136
	v_add_u32_e32 v189, 0x30000, v189
	s_add_i32 s6, s3, 0x7000
	s_lshl_b32 s6, s6, 12
	s_add_u32 s4, s18, s6
	s_addc_u32 s5, s19, 0
	global_load_dwordx4 v[2:5], v140, s[4:5] nt
	global_load_dwordx4 v[6:9], v140, s[4:5] offset:1024 nt
	global_load_dwordx4 v[10:13], v140, s[4:5] offset:2048 nt
	global_load_dwordx4 v[14:17], v140, s[4:5] offset:3072 nt
	global_load_dwordx4 v[18:21], v141, s[4:5] nt
	global_load_dwordx4 v[22:25], v141, s[4:5] offset:1024 nt
	global_load_dwordx4 v[26:29], v141, s[4:5] offset:2048 nt
	global_load_dwordx4 v[30:33], v141, s[4:5] offset:3072 nt
	global_load_dwordx4 v[34:37], v142, s[4:5] nt
	global_load_dwordx4 v[38:41], v142, s[4:5] offset:1024 nt
	global_load_dwordx4 v[42:45], v142, s[4:5] offset:2048 nt
	global_load_dwordx4 v[46:49], v142, s[4:5] offset:3072 nt
	global_load_dwordx4 v[50:53], v143, s[4:5] nt
	global_load_dwordx4 v[54:57], v143, s[4:5] offset:1024 nt
	global_load_dwordx4 v[58:61], v143, s[4:5] offset:2048 nt
	global_load_dwordx4 v[62:65], v143, s[4:5] offset:3072 nt
	s_waitcnt vmcnt(0)
; __device__ void p0_xconv(const Args& a) {
;     ...
;         for (int r = 0; r < 4; ++r) {
;             const int row = row0 + r * nwv;
;             if (row < MROWS) {
;                 float ss = 0.f;
; #pragma unroll
;                 for (int i = 0; i < 4; ++i) {
;                     const f32x4 x = v[r][i];
;                     ss += (x[0] * x[0] + x[1] * x[1]) + (x[2] * x[2] + x[3] * x[3]);
;                     f16x4 h; h[0] = (f16)x[0]; h[1] = (f16)x[1]; h[2] = (f16)x[2]; h[3] = (f16)x[3];
;                     *(f16x4*)(XH + (size_t)row * DM + i * 256 + lane * 4) = h;
;                 }
; #pragma unroll
;                 for (int o = 1; o < 64; o <<= 1) ss += __shfl_xor(ss, o);
;                 if (lane < 16) SS[(size_t)row * 16 + lane] = (lane == 0) ? ss : 0.f;
	s_add_i32 s6, s3, 0xb000
	s_lshl_b32 s7, s6, 11
	s_add_u32 s10, s40, s7
	s_addc_u32 s11, s41, 0
	s_lshl_b32 s7, s6, 6
	s_add_u32 s6, s40, s7
	s_addc_u32 s7, s41, 0
	s_add_u32 s6, s6, 0x1f800000
	s_addc_u32 s7, s7, 0
	v_mul_f32_e32 v150, v3, v3
	v_mul_f32_e32 v151, v5, v5
	v_fmac_f32_e32 v150, v2, v2
	v_fmac_f32_e32 v151, v4, v4
	v_add_f32_e32 v160, v150, v151
	v_cvt_pk_f16_f32 v170, v2, v3
	v_cvt_pk_f16_f32 v171, v4, v5
	v_mul_f32_e32 v150, v7, v7
	v_mul_f32_e32 v151, v9, v9
	v_fmac_f32_e32 v150, v6, v6
	v_fmac_f32_e32 v151, v8, v8
	v_add_f32_e32 v152, v150, v151
	v_add_f32_e32 v160, v160, v152
	v_cvt_pk_f16_f32 v172, v6, v7
	v_cvt_pk_f16_f32 v173, v8, v9
	v_mul_f32_e32 v150, v11, v11
	v_mul_f32_e32 v151, v13, v13
	v_fmac_f32_e32 v150, v10, v10
	v_fmac_f32_e32 v151, v12, v12
	v_add_f32_e32 v152, v150, v151
	v_add_f32_e32 v160, v160, v152
	v_cvt_pk_f16_f32 v174, v10, v11
	v_cvt_pk_f16_f32 v175, v12, v13
	v_mul_f32_e32 v150, v15, v15
	v_mul_f32_e32 v151, v17, v17
	v_fmac_f32_e32 v150, v14, v14
	v_fmac_f32_e32 v151, v16, v16
	v_add_f32_e32 v152, v150, v151
	v_add_f32_e32 v160, v160, v152
	v_cvt_pk_f16_f32 v176, v14, v15
	v_cvt_pk_f16_f32 v177, v16, v17
	global_store_dwordx2 v144, v[170:171], s[10:11]
	global_store_dwordx2 v144, v[172:173], s[10:11] offset:512
	global_store_dwordx2 v144, v[174:175], s[10:11] offset:1024
	global_store_dwordx2 v144, v[176:177], s[10:11] offset:1536
	v_mul_f32_e32 v150, v19, v19
	v_mul_f32_e32 v151, v21, v21
	v_fmac_f32_e32 v150, v18, v18
	v_fmac_f32_e32 v151, v20, v20
	v_add_f32_e32 v161, v150, v151
	v_cvt_pk_f16_f32 v178, v18, v19
	v_cvt_pk_f16_f32 v179, v20, v21
	v_mul_f32_e32 v150, v23, v23
	v_mul_f32_e32 v151, v25, v25
	v_fmac_f32_e32 v150, v22, v22
	v_fmac_f32_e32 v151, v24, v24
	v_add_f32_e32 v152, v150, v151
	v_add_f32_e32 v161, v161, v152
	v_cvt_pk_f16_f32 v180, v22, v23
	v_cvt_pk_f16_f32 v181, v24, v25
	v_mul_f32_e32 v150, v27, v27
	v_mul_f32_e32 v151, v29, v29
	v_fmac_f32_e32 v150, v26, v26
	v_fmac_f32_e32 v151, v28, v28
	v_add_f32_e32 v152, v150, v151
	v_add_f32_e32 v161, v161, v152
	v_cvt_pk_f16_f32 v182, v26, v27
	v_cvt_pk_f16_f32 v183, v28, v29
	v_mul_f32_e32 v150, v31, v31
	v_mul_f32_e32 v151, v33, v33
	v_fmac_f32_e32 v150, v30, v30
	v_fmac_f32_e32 v151, v32, v32
	v_add_f32_e32 v152, v150, v151
	v_add_f32_e32 v161, v161, v152
	v_cvt_pk_f16_f32 v184, v30, v31
	v_cvt_pk_f16_f32 v185, v32, v33
	global_store_dwordx2 v145, v[178:179], s[10:11]
	global_store_dwordx2 v145, v[180:181], s[10:11] offset:512
	global_store_dwordx2 v145, v[182:183], s[10:11] offset:1024
	global_store_dwordx2 v145, v[184:185], s[10:11] offset:1536
	v_mul_f32_e32 v150, v35, v35
	v_mul_f32_e32 v151, v37, v37
	v_fmac_f32_e32 v150, v34, v34
	v_fmac_f32_e32 v151, v36, v36
	v_add_f32_e32 v162, v150, v151
	v_cvt_pk_f16_f32 v170, v34, v35
	v_cvt_pk_f16_f32 v171, v36, v37
	v_mul_f32_e32 v150, v39, v39
	v_mul_f32_e32 v151, v41, v41
	v_fmac_f32_e32 v150, v38, v38
	v_fmac_f32_e32 v151, v40, v40
	v_add_f32_e32 v152, v150, v151
	v_add_f32_e32 v162, v162, v152
	v_cvt_pk_f16_f32 v172, v38, v39
	v_cvt_pk_f16_f32 v173, v40, v41
	v_mul_f32_e32 v150, v43, v43
	v_mul_f32_e32 v151, v45, v45
	v_fmac_f32_e32 v150, v42, v42
	v_fmac_f32_e32 v151, v44, v44
	v_add_f32_e32 v152, v150, v151
	v_add_f32_e32 v162, v162, v152
	v_cvt_pk_f16_f32 v174, v42, v43
	v_cvt_pk_f16_f32 v175, v44, v45
	v_mul_f32_e32 v150, v47, v47
	v_mul_f32_e32 v151, v49, v49
	v_fmac_f32_e32 v150, v46, v46
	v_fmac_f32_e32 v151, v48, v48
	v_add_f32_e32 v152, v150, v151
	v_add_f32_e32 v162, v162, v152
	v_cvt_pk_f16_f32 v176, v46, v47
	v_cvt_pk_f16_f32 v177, v48, v49
	global_store_dwordx2 v146, v[170:171], s[10:11]
	global_store_dwordx2 v146, v[172:173], s[10:11] offset:512
	global_store_dwordx2 v146, v[174:175], s[10:11] offset:1024
	global_store_dwordx2 v146, v[176:177], s[10:11] offset:1536
	v_mul_f32_e32 v150, v51, v51
	v_mul_f32_e32 v151, v53, v53
	v_fmac_f32_e32 v150, v50, v50
	v_fmac_f32_e32 v151, v52, v52
	v_add_f32_e32 v163, v150, v151
	v_cvt_pk_f16_f32 v178, v50, v51
	v_cvt_pk_f16_f32 v179, v52, v53
	v_mul_f32_e32 v150, v55, v55
	v_mul_f32_e32 v151, v57, v57
	v_fmac_f32_e32 v150, v54, v54
	v_fmac_f32_e32 v151, v56, v56
	v_add_f32_e32 v152, v150, v151
	v_add_f32_e32 v163, v163, v152
	v_cvt_pk_f16_f32 v180, v54, v55
	v_cvt_pk_f16_f32 v181, v56, v57
	v_mul_f32_e32 v150, v59, v59
	v_mul_f32_e32 v151, v61, v61
	v_fmac_f32_e32 v150, v58, v58
	v_fmac_f32_e32 v151, v60, v60
	v_add_f32_e32 v152, v150, v151
	v_add_f32_e32 v163, v163, v152
	v_cvt_pk_f16_f32 v182, v58, v59
	v_cvt_pk_f16_f32 v183, v60, v61
	v_mul_f32_e32 v150, v63, v63
	v_mul_f32_e32 v151, v65, v65
	v_fmac_f32_e32 v150, v62, v62
	v_fmac_f32_e32 v151, v64, v64
	v_add_f32_e32 v152, v150, v151
	v_add_f32_e32 v163, v163, v152
	v_cvt_pk_f16_f32 v184, v62, v63
	v_cvt_pk_f16_f32 v185, v64, v65
	global_store_dwordx2 v147, v[178:179], s[10:11]
	global_store_dwordx2 v147, v[180:181], s[10:11] offset:512
	global_store_dwordx2 v147, v[182:183], s[10:11] offset:1024
	global_store_dwordx2 v147, v[184:185], s[10:11] offset:1536
	ds_bpermute_b32 v164, v130, v160
	ds_bpermute_b32 v165, v130, v161
	ds_bpermute_b32 v166, v130, v162
	ds_bpermute_b32 v167, v130, v163
	s_waitcnt lgkmcnt(0)
	v_add_f32_e32 v160, v160, v164
	v_add_f32_e32 v161, v161, v165
	v_add_f32_e32 v162, v162, v166
	v_add_f32_e32 v163, v163, v167
	ds_bpermute_b32 v164, v131, v160
	ds_bpermute_b32 v165, v131, v161
	ds_bpermute_b32 v166, v131, v162
	ds_bpermute_b32 v167, v131, v163
	s_waitcnt lgkmcnt(0)
	v_add_f32_e32 v160, v160, v164
	v_add_f32_e32 v161, v161, v165
	v_add_f32_e32 v162, v162, v166
	v_add_f32_e32 v163, v163, v167
	ds_bpermute_b32 v164, v132, v160
	ds_bpermute_b32 v165, v132, v161
	ds_bpermute_b32 v166, v132, v162
	ds_bpermute_b32 v167, v132, v163
	s_waitcnt lgkmcnt(0)
; __device__ void p0_xconv(const Args& a) {
;     ...
;     for (int row0 = (int)blockIdx.x * 8 + wv; row0 < MROWS; row0 += 4 * nwv) {
;         f32x4 v[4][4];
; #pragma unroll
;         for (int r = 0; r < 4; ++r) {
;             const int row = row0 + r * nwv;
;             if (row < MROWS) {
;                 const float* src = (row < ROWS_PROMPT) ? a.x_prompt + (size_t)row * DM : a.x_sample + (size_t)(row - ROWS_PROMPT) * DM;
; #pragma unroll
;                 for (int i = 0; i < 4; ++i) v[r][i] = __builtin_nontemporal_load((const f32x4*)(src + i * 256 + lane * 4));
;             }
;         }
;     ...
;                 float ss = 0.f;
; #pragma unroll
;                 for (int i = 0; i < 4; ++i) {
;                     const f32x4 x = v[r][i];
;                     ss += (x[0] * x[0] + x[1] * x[1]) + (x[2] * x[2] + x[3] * x[3]);
;                     f16x4 h; h[0] = (f16)x[0]; h[1] = (f16)x[1]; h[2] = (f16)x[2]; h[3] = (f16)x[3];
;                     *(f16x4*)(XH + (size_t)row * DM + i * 256 + lane * 4) = h;
;                 }
; #pragma unroll
;                 for (int o = 1; o < 64; o <<= 1) ss += __shfl_xor(ss, o);
;                 if (lane < 16) SS[(size_t)row * 16 + lane] = (lane == 0) ? ss : 0.f;
	v_add_f32_e32 v160, v160, v164
	v_add_f32_e32 v161, v161, v165
	v_add_f32_e32 v162, v162, v166
	v_add_f32_e32 v163, v163, v167
	ds_bpermute_b32 v164, v133, v160
	ds_bpermute_b32 v165, v133, v161
	ds_bpermute_b32 v166, v133, v162
	ds_bpermute_b32 v167, v133, v163
	s_waitcnt lgkmcnt(0)
	v_add_f32_e32 v160, v160, v164
	v_add_f32_e32 v161, v161, v165
	v_add_f32_e32 v162, v162, v166
	v_add_f32_e32 v163, v163, v167
	ds_bpermute_b32 v164, v134, v160
	ds_bpermute_b32 v165, v134, v161
	ds_bpermute_b32 v166, v134, v162
	ds_bpermute_b32 v167, v134, v163
	s_waitcnt lgkmcnt(0)
	v_add_f32_e32 v160, v160, v164
	v_add_f32_e32 v161, v161, v165
	v_add_f32_e32 v162, v162, v166
	v_add_f32_e32 v163, v163, v167
	ds_bpermute_b32 v164, v135, v160
	ds_bpermute_b32 v165, v135, v161
	ds_bpermute_b32 v166, v135, v162
	ds_bpermute_b32 v167, v135, v163
	s_waitcnt lgkmcnt(0)
	v_add_f32_e32 v160, v160, v164
	v_add_f32_e32 v161, v161, v165
	v_add_f32_e32 v162, v162, v166
	v_add_f32_e32 v163, v163, v167
	v_cndmask_b32_e64 v164, 0, v160, s[12:13]
	v_cndmask_b32_e64 v165, 0, v161, s[12:13]
	v_cndmask_b32_e64 v166, 0, v162, s[12:13]
	v_cndmask_b32_e64 v167, 0, v163, s[12:13]
	s_mov_b64 exec, 0xffff
	global_store_dword v186, v164, s[6:7]
	global_store_dword v187, v165, s[6:7]
	global_store_dword v188, v166, s[6:7]
	global_store_dword v189, v167, s[6:7]
	s_mov_b64 exec, -1
	s_barrier
	s_branch .LBB0_112
.Lpw_x:
	s_barrier
	v_and_b32_e32 v136, 63, v0
	v_lshrrev_b32_e32 v137, 6, v0
	s_nop 0
	v_readfirstlane_b32 s3, v137
	s_nop 3
	s_lshl_b32 s4, s2, 2
	s_add_i32 s3, s3, s4
	s_add_i32 s3, s3, -4
	s_mov_b64 s[12:13], 1
	v_xor_b32_e32 v130, 1, v136
	v_lshlrev_b32_e32 v130, 2, v130
	v_xor_b32_e32 v131, 2, v136
	v_lshlrev_b32_e32 v131, 2, v131
	v_xor_b32_e32 v132, 4, v136
	v_lshlrev_b32_e32 v132, 2, v132
	v_xor_b32_e32 v133, 8, v136
	v_lshlrev_b32_e32 v133, 2, v133
	v_xor_b32_e32 v134, 16, v136
	v_lshlrev_b32_e32 v134, 2, v134
	v_xor_b32_e32 v135, 32, v136
	v_lshlrev_b32_e32 v135, 2, v135
	v_lshlrev_b32_e32 v140, 4, v136
	v_lshlrev_b32_e32 v144, 3, v136
	v_lshlrev_b32_e32 v186, 2, v136
	v_lshlrev_b32_e32 v141, 4, v136
	v_add_u32_e32 v141, 0x400000, v141
	v_lshlrev_b32_e32 v145, 3, v136
	v_add_u32_e32 v145, 0x200000, v145
	v_lshlrev_b32_e32 v187, 2, v136
	v_add_u32_e32 v187, 0x10000, v187
	v_lshlrev_b32_e32 v142, 4, v136
	v_add_u32_e32 v142, 0x800000, v142
	v_lshlrev_b32_e32 v146, 3, v136
	v_add_u32_e32 v146, 0x400000, v146
	v_lshlrev_b32_e32 v188, 2, v136
	v_add_u32_e32 v188, 0x20000, v188
	v_lshlrev_b32_e32 v143, 4, v136
	v_add_u32_e32 v143, 0xc00000, v143
	v_lshlrev_b32_e32 v147, 3, v136
	v_add_u32_e32 v147, 0x600000, v147
	v_lshlrev_b32_e32 v189, 2, v136
	v_add_u32_e32 v189, 0x30000, v189
	s_add_i32 s6, s3, 0x4000
	s_lshl_b32 s6, s6, 12
	s_add_u32 s4, s18, s6
	s_addc_u32 s5, s19, 0
	global_load_dwordx4 v[2:5], v140, s[4:5] nt
	global_load_dwordx4 v[6:9], v140, s[4:5] offset:1024 nt
	global_load_dwordx4 v[10:13], v140, s[4:5] offset:2048 nt
	global_load_dwordx4 v[14:17], v140, s[4:5] offset:3072 nt
	global_load_dwordx4 v[18:21], v141, s[4:5] nt
	global_load_dwordx4 v[22:25], v141, s[4:5] offset:1024 nt
	global_load_dwordx4 v[26:29], v141, s[4:5] offset:2048 nt
	global_load_dwordx4 v[30:33], v141, s[4:5] offset:3072 nt
	global_load_dwordx4 v[34:37], v142, s[4:5] nt
	global_load_dwordx4 v[38:41], v142, s[4:5] offset:1024 nt
	global_load_dwordx4 v[42:45], v142, s[4:5] offset:2048 nt
	global_load_dwordx4 v[46:49], v142, s[4:5] offset:3072 nt
	global_load_dwordx4 v[50:53], v143, s[4:5] nt
	global_load_dwordx4 v[54:57], v143, s[4:5] offset:1024 nt
	global_load_dwordx4 v[58:61], v143, s[4:5] offset:2048 nt
	global_load_dwordx4 v[62:65], v143, s[4:5] offset:3072 nt
	s_add_i32 s6, s3, 0x5000
	s_lshl_b32 s6, s6, 12
	s_add_u32 s4, s18, s6
	s_addc_u32 s5, s19, 0
	global_load_dwordx4 v[66:69], v140, s[4:5] nt
	global_load_dwordx4 v[70:73], v140, s[4:5] offset:1024 nt
	global_load_dwordx4 v[74:77], v140, s[4:5] offset:2048 nt
	global_load_dwordx4 v[78:81], v140, s[4:5] offset:3072 nt
	global_load_dwordx4 v[82:85], v141, s[4:5] nt
	global_load_dwordx4 v[86:89], v141, s[4:5] offset:1024 nt
	global_load_dwordx4 v[90:93], v141, s[4:5] offset:2048 nt
	global_load_dwordx4 v[94:97], v141, s[4:5] offset:3072 nt
	global_load_dwordx4 v[98:101], v142, s[4:5] nt
	global_load_dwordx4 v[102:105], v142, s[4:5] offset:1024 nt
	global_load_dwordx4 v[106:109], v142, s[4:5] offset:2048 nt
	global_load_dwordx4 v[110:113], v142, s[4:5] offset:3072 nt
	global_load_dwordx4 v[114:117], v143, s[4:5] nt
	global_load_dwordx4 v[118:121], v143, s[4:5] offset:1024 nt
	global_load_dwordx4 v[122:125], v143, s[4:5] offset:2048 nt
	global_load_dwordx4 v[126:129], v143, s[4:5] offset:3072 nt
	s_waitcnt vmcnt(16)
; __device__ void p0_xconv(const Args& a) {
;     ...
;         for (int r = 0; r < 4; ++r) {
;             const int row = row0 + r * nwv;
;             if (row < MROWS) {
;                 float ss = 0.f;
; #pragma unroll
;                 for (int i = 0; i < 4; ++i) {
;                     const f32x4 x = v[r][i];
;                     ss += (x[0] * x[0] + x[1] * x[1]) + (x[2] * x[2] + x[3] * x[3]);
;                     f16x4 h; h[0] = (f16)x[0]; h[1] = (f16)x[1]; h[2] = (f16)x[2]; h[3] = (f16)x[3];
;                     *(f16x4*)(XH + (size_t)row * DM + i * 256 + lane * 4) = h;
;                 }
; #pragma unroll
;                 for (int o = 1; o < 64; o <<= 1) ss += __shfl_xor(ss, o);
;                 if (lane < 16) SS[(size_t)row * 16 + lane] = (lane == 0) ? ss : 0.f;
	s_add_i32 s6, s3, 0x8000
	s_lshl_b32 s7, s6, 11
	s_add_u32 s10, s40, s7
	s_addc_u32 s11, s41, 0
	s_lshl_b32 s7, s6, 6
	s_add_u32 s6, s40, s7
	s_addc_u32 s7, s41, 0
	s_add_u32 s6, s6, 0x1f800000
	s_addc_u32 s7, s7, 0
	v_mul_f32_e32 v150, v3, v3
	v_mul_f32_e32 v151, v5, v5
	v_fmac_f32_e32 v150, v2, v2
	v_fmac_f32_e32 v151, v4, v4
	v_add_f32_e32 v160, v150, v151
	v_cvt_pk_f16_f32 v170, v2, v3
	v_cvt_pk_f16_f32 v171, v4, v5
	v_mul_f32_e32 v150, v7, v7
	v_mul_f32_e32 v151, v9, v9
	v_fmac_f32_e32 v150, v6, v6
	v_fmac_f32_e32 v151, v8, v8
	v_add_f32_e32 v152, v150, v151
	v_add_f32_e32 v160, v160, v152
	v_cvt_pk_f16_f32 v172, v6, v7
	v_cvt_pk_f16_f32 v173, v8, v9
	v_mul_f32_e32 v150, v11, v11
	v_mul_f32_e32 v151, v13, v13
	v_fmac_f32_e32 v150, v10, v10
	v_fmac_f32_e32 v151, v12, v12
	v_add_f32_e32 v152, v150, v151
	v_add_f32_e32 v160, v160, v152
	v_cvt_pk_f16_f32 v174, v10, v11
	v_cvt_pk_f16_f32 v175, v12, v13
	v_mul_f32_e32 v150, v15, v15
	v_mul_f32_e32 v151, v17, v17
	v_fmac_f32_e32 v150, v14, v14
	v_fmac_f32_e32 v151, v16, v16
	v_add_f32_e32 v152, v150, v151
	v_add_f32_e32 v160, v160, v152
	v_cvt_pk_f16_f32 v176, v14, v15
	v_cvt_pk_f16_f32 v177, v16, v17
	global_store_dwordx2 v144, v[170:171], s[10:11]
	global_store_dwordx2 v144, v[172:173], s[10:11] offset:512
	global_store_dwordx2 v144, v[174:175], s[10:11] offset:1024
	global_store_dwordx2 v144, v[176:177], s[10:11] offset:1536
	v_mul_f32_e32 v150, v19, v19
	v_mul_f32_e32 v151, v21, v21
	v_fmac_f32_e32 v150, v18, v18
	v_fmac_f32_e32 v151, v20, v20
	v_add_f32_e32 v161, v150, v151
	v_cvt_pk_f16_f32 v178, v18, v19
	v_cvt_pk_f16_f32 v179, v20, v21
	v_mul_f32_e32 v150, v23, v23
	v_mul_f32_e32 v151, v25, v25
	v_fmac_f32_e32 v150, v22, v22
	v_fmac_f32_e32 v151, v24, v24
	v_add_f32_e32 v152, v150, v151
	v_add_f32_e32 v161, v161, v152
	v_cvt_pk_f16_f32 v180, v22, v23
	v_cvt_pk_f16_f32 v181, v24, v25
	v_mul_f32_e32 v150, v27, v27
	v_mul_f32_e32 v151, v29, v29
	v_fmac_f32_e32 v150, v26, v26
	v_fmac_f32_e32 v151, v28, v28
	v_add_f32_e32 v152, v150, v151
	v_add_f32_e32 v161, v161, v152
	v_cvt_pk_f16_f32 v182, v26, v27
	v_cvt_pk_f16_f32 v183, v28, v29
	v_mul_f32_e32 v150, v31, v31
	v_mul_f32_e32 v151, v33, v33
	v_fmac_f32_e32 v150, v30, v30
	v_fmac_f32_e32 v151, v32, v32
	v_add_f32_e32 v152, v150, v151
	v_add_f32_e32 v161, v161, v152
	v_cvt_pk_f16_f32 v184, v30, v31
	v_cvt_pk_f16_f32 v185, v32, v33
	global_store_dwordx2 v145, v[178:179], s[10:11]
	global_store_dwordx2 v145, v[180:181], s[10:11] offset:512
	global_store_dwordx2 v145, v[182:183], s[10:11] offset:1024
	global_store_dwordx2 v145, v[184:185], s[10:11] offset:1536
	v_mul_f32_e32 v150, v35, v35
	v_mul_f32_e32 v151, v37, v37
	v_fmac_f32_e32 v150, v34, v34
	v_fmac_f32_e32 v151, v36, v36
	v_add_f32_e32 v162, v150, v151
	v_cvt_pk_f16_f32 v170, v34, v35
	v_cvt_pk_f16_f32 v171, v36, v37
	v_mul_f32_e32 v150, v39, v39
	v_mul_f32_e32 v151, v41, v41
	v_fmac_f32_e32 v150, v38, v38
	v_fmac_f32_e32 v151, v40, v40
	v_add_f32_e32 v152, v150, v151
	v_add_f32_e32 v162, v162, v152
	v_cvt_pk_f16_f32 v172, v38, v39
	v_cvt_pk_f16_f32 v173, v40, v41
	v_mul_f32_e32 v150, v43, v43
	v_mul_f32_e32 v151, v45, v45
	v_fmac_f32_e32 v150, v42, v42
	v_fmac_f32_e32 v151, v44, v44
	v_add_f32_e32 v152, v150, v151
	v_add_f32_e32 v162, v162, v152
	v_cvt_pk_f16_f32 v174, v42, v43
	v_cvt_pk_f16_f32 v175, v44, v45
	v_mul_f32_e32 v150, v47, v47
	v_mul_f32_e32 v151, v49, v49
	v_fmac_f32_e32 v150, v46, v46
	v_fmac_f32_e32 v151, v48, v48
	v_add_f32_e32 v152, v150, v151
	v_add_f32_e32 v162, v162, v152
	v_cvt_pk_f16_f32 v176, v46, v47
	v_cvt_pk_f16_f32 v177, v48, v49
	global_store_dwordx2 v146, v[170:171], s[10:11]
	global_store_dwordx2 v146, v[172:173], s[10:11] offset:512
	global_store_dwordx2 v146, v[174:175], s[10:11] offset:1024
	global_store_dwordx2 v146, v[176:177], s[10:11] offset:1536
	v_mul_f32_e32 v150, v51, v51
	v_mul_f32_e32 v151, v53, v53
	v_fmac_f32_e32 v150, v50, v50
	v_fmac_f32_e32 v151, v52, v52
	v_add_f32_e32 v163, v150, v151
	v_cvt_pk_f16_f32 v178, v50, v51
	v_cvt_pk_f16_f32 v179, v52, v53
	v_mul_f32_e32 v150, v55, v55
	v_mul_f32_e32 v151, v57, v57
	v_fmac_f32_e32 v150, v54, v54
	v_fmac_f32_e32 v151, v56, v56
	v_add_f32_e32 v152, v150, v151
	v_add_f32_e32 v163, v163, v152
	v_cvt_pk_f16_f32 v180, v54, v55
	v_cvt_pk_f16_f32 v181, v56, v57
	v_mul_f32_e32 v150, v59, v59
	v_mul_f32_e32 v151, v61, v61
	v_fmac_f32_e32 v150, v58, v58
	v_fmac_f32_e32 v151, v60, v60
	v_add_f32_e32 v152, v150, v151
	v_add_f32_e32 v163, v163, v152
	v_cvt_pk_f16_f32 v182, v58, v59
	v_cvt_pk_f16_f32 v183, v60, v61
	v_mul_f32_e32 v150, v63, v63
	v_mul_f32_e32 v151, v65, v65
	v_fmac_f32_e32 v150, v62, v62
	v_fmac_f32_e32 v151, v64, v64
	v_add_f32_e32 v152, v150, v151
	v_add_f32_e32 v163, v163, v152
	v_cvt_pk_f16_f32 v184, v62, v63
	v_cvt_pk_f16_f32 v185, v64, v65
	global_store_dwordx2 v147, v[178:179], s[10:11]
	global_store_dwordx2 v147, v[180:181], s[10:11] offset:512
	global_store_dwordx2 v147, v[182:183], s[10:11] offset:1024
	global_store_dwordx2 v147, v[184:185], s[10:11] offset:1536
	ds_bpermute_b32 v164, v130, v160
	ds_bpermute_b32 v165, v130, v161
	ds_bpermute_b32 v166, v130, v162
	ds_bpermute_b32 v167, v130, v163
	s_waitcnt lgkmcnt(0)
	v_add_f32_e32 v160, v160, v164
	v_add_f32_e32 v161, v161, v165
	v_add_f32_e32 v162, v162, v166
	v_add_f32_e32 v163, v163, v167
	ds_bpermute_b32 v164, v131, v160
	ds_bpermute_b32 v165, v131, v161
	ds_bpermute_b32 v166, v131, v162
	ds_bpermute_b32 v167, v131, v163
	s_waitcnt lgkmcnt(0)
	v_add_f32_e32 v160, v160, v164
	v_add_f32_e32 v161, v161, v165
	v_add_f32_e32 v162, v162, v166
	v_add_f32_e32 v163, v163, v167
	ds_bpermute_b32 v164, v132, v160
	ds_bpermute_b32 v165, v132, v161
	ds_bpermute_b32 v166, v132, v162
	ds_bpermute_b32 v167, v132, v163
	s_waitcnt lgkmcnt(0)
; __device__ void p0_xconv(const Args& a) {
;     ...
;     for (int row0 = (int)blockIdx.x * 8 + wv; row0 < MROWS; row0 += 4 * nwv) {
;         f32x4 v[4][4];
; #pragma unroll
;         for (int r = 0; r < 4; ++r) {
;             const int row = row0 + r * nwv;
;             if (row < MROWS) {
;                 const float* src = (row < ROWS_PROMPT) ? a.x_prompt + (size_t)row * DM : a.x_sample + (size_t)(row - ROWS_PROMPT) * DM;
; #pragma unroll
;                 for (int i = 0; i < 4; ++i) v[r][i] = __builtin_nontemporal_load((const f32x4*)(src + i * 256 + lane * 4));
;             }
;         }
; #pragma unroll
;         for (int r = 0; r < 4; ++r) {
;             const int row = row0 + r * nwv;
;             if (row < MROWS) {
;                 float ss = 0.f;
; #pragma unroll
;                 for (int i = 0; i < 4; ++i) {
;                     const f32x4 x = v[r][i];
;                     ss += (x[0] * x[0] + x[1] * x[1]) + (x[2] * x[2] + x[3] * x[3]);
;                     f16x4 h; h[0] = (f16)x[0]; h[1] = (f16)x[1]; h[2] = (f16)x[2]; h[3] = (f16)x[3];
;                     *(f16x4*)(XH + (size_t)row * DM + i * 256 + lane * 4) = h;
;                 }
; #pragma unroll
;                 for (int o = 1; o < 64; o <<= 1) ss += __shfl_xor(ss, o);
;                 if (lane < 16) SS[(size_t)row * 16 + lane] = (lane == 0) ? ss : 0.f;
	v_add_f32_e32 v160, v160, v164
	v_add_f32_e32 v161, v161, v165
	v_add_f32_e32 v162, v162, v166
	v_add_f32_e32 v163, v163, v167
	ds_bpermute_b32 v164, v133, v160
	ds_bpermute_b32 v165, v133, v161
	ds_bpermute_b32 v166, v133, v162
	ds_bpermute_b32 v167, v133, v163
	s_waitcnt lgkmcnt(0)
	v_add_f32_e32 v160, v160, v164
	v_add_f32_e32 v161, v161, v165
	v_add_f32_e32 v162, v162, v166
	v_add_f32_e32 v163, v163, v167
	ds_bpermute_b32 v164, v134, v160
	ds_bpermute_b32 v165, v134, v161
	ds_bpermute_b32 v166, v134, v162
	ds_bpermute_b32 v167, v134, v163
	s_waitcnt lgkmcnt(0)
	v_add_f32_e32 v160, v160, v164
	v_add_f32_e32 v161, v161, v165
	v_add_f32_e32 v162, v162, v166
	v_add_f32_e32 v163, v163, v167
	ds_bpermute_b32 v164, v135, v160
	ds_bpermute_b32 v165, v135, v161
	ds_bpermute_b32 v166, v135, v162
	ds_bpermute_b32 v167, v135, v163
	s_waitcnt lgkmcnt(0)
	v_add_f32_e32 v160, v160, v164
	v_add_f32_e32 v161, v161, v165
	v_add_f32_e32 v162, v162, v166
	v_add_f32_e32 v163, v163, v167
	v_cndmask_b32_e64 v164, 0, v160, s[12:13]
	v_cndmask_b32_e64 v165, 0, v161, s[12:13]
	v_cndmask_b32_e64 v166, 0, v162, s[12:13]
	v_cndmask_b32_e64 v167, 0, v163, s[12:13]
	s_mov_b64 exec, 0xffff
	global_store_dword v186, v164, s[6:7]
	global_store_dword v187, v165, s[6:7]
	global_store_dword v188, v166, s[6:7]
	global_store_dword v189, v167, s[6:7]
	s_mov_b64 exec, -1
	s_barrier
	s_add_i32 s6, s3, 0x6000
	s_lshl_b32 s6, s6, 12
	s_add_u32 s4, s18, s6
	s_addc_u32 s5, s19, 0
	global_load_dwordx4 v[2:5], v140, s[4:5] nt
	global_load_dwordx4 v[6:9], v140, s[4:5] offset:1024 nt
	global_load_dwordx4 v[10:13], v140, s[4:5] offset:2048 nt
	global_load_dwordx4 v[14:17], v140, s[4:5] offset:3072 nt
	global_load_dwordx4 v[18:21], v141, s[4:5] nt
	global_load_dwordx4 v[22:25], v141, s[4:5] offset:1024 nt
	global_load_dwordx4 v[26:29], v141, s[4:5] offset:2048 nt
	global_load_dwordx4 v[30:33], v141, s[4:5] offset:3072 nt
	global_load_dwordx4 v[34:37], v142, s[4:5] nt
	global_load_dwordx4 v[38:41], v142, s[4:5] offset:1024 nt
	global_load_dwordx4 v[42:45], v142, s[4:5] offset:2048 nt
	global_load_dwordx4 v[46:49], v142, s[4:5] offset:3072 nt
	global_load_dwordx4 v[50:53], v143, s[4:5] nt
	global_load_dwordx4 v[54:57], v143, s[4:5] offset:1024 nt
	global_load_dwordx4 v[58:61], v143, s[4:5] offset:2048 nt
	global_load_dwordx4 v[62:65], v143, s[4:5] offset:3072 nt
	s_waitcnt vmcnt(36)
	s_add_i32 s6, s3, 0x9000
	s_lshl_b32 s7, s6, 11
	s_add_u32 s10, s40, s7
	s_addc_u32 s11, s41, 0
	s_lshl_b32 s7, s6, 6
	s_add_u32 s6, s40, s7
	s_addc_u32 s7, s41, 0
	s_add_u32 s6, s6, 0x1f800000
	s_addc_u32 s7, s7, 0
	v_mul_f32_e32 v150, v67, v67
	v_mul_f32_e32 v151, v69, v69
	v_fmac_f32_e32 v150, v66, v66
	v_fmac_f32_e32 v151, v68, v68
	v_add_f32_e32 v160, v150, v151
	v_cvt_pk_f16_f32 v170, v66, v67
	v_cvt_pk_f16_f32 v171, v68, v69
	v_mul_f32_e32 v150, v71, v71
	v_mul_f32_e32 v151, v73, v73
	v_fmac_f32_e32 v150, v70, v70
	v_fmac_f32_e32 v151, v72, v72
	v_add_f32_e32 v152, v150, v151
	v_add_f32_e32 v160, v160, v152
	v_cvt_pk_f16_f32 v172, v70, v71
	v_cvt_pk_f16_f32 v173, v72, v73
	v_mul_f32_e32 v150, v75, v75
	v_mul_f32_e32 v151, v77, v77
	v_fmac_f32_e32 v150, v74, v74
	v_fmac_f32_e32 v151, v76, v76
	v_add_f32_e32 v152, v150, v151
	v_add_f32_e32 v160, v160, v152
	v_cvt_pk_f16_f32 v174, v74, v75
	v_cvt_pk_f16_f32 v175, v76, v77
	v_mul_f32_e32 v150, v79, v79
	v_mul_f32_e32 v151, v81, v81
	v_fmac_f32_e32 v150, v78, v78
	v_fmac_f32_e32 v151, v80, v80
	v_add_f32_e32 v152, v150, v151
	v_add_f32_e32 v160, v160, v152
	v_cvt_pk_f16_f32 v176, v78, v79
	v_cvt_pk_f16_f32 v177, v80, v81
	global_store_dwordx2 v144, v[170:171], s[10:11]
	global_store_dwordx2 v144, v[172:173], s[10:11] offset:512
	global_store_dwordx2 v144, v[174:175], s[10:11] offset:1024
	global_store_dwordx2 v144, v[176:177], s[10:11] offset:1536
	v_mul_f32_e32 v150, v83, v83
	v_mul_f32_e32 v151, v85, v85
	v_fmac_f32_e32 v150, v82, v82
	v_fmac_f32_e32 v151, v84, v84
	v_add_f32_e32 v161, v150, v151
	v_cvt_pk_f16_f32 v178, v82, v83
	v_cvt_pk_f16_f32 v179, v84, v85
	v_mul_f32_e32 v150, v87, v87
	v_mul_f32_e32 v151, v89, v89
	v_fmac_f32_e32 v150, v86, v86
	v_fmac_f32_e32 v151, v88, v88
	v_add_f32_e32 v152, v150, v151
	v_add_f32_e32 v161, v161, v152
	v_cvt_pk_f16_f32 v180, v86, v87
	v_cvt_pk_f16_f32 v181, v88, v89
	v_mul_f32_e32 v150, v91, v91
	v_mul_f32_e32 v151, v93, v93
	v_fmac_f32_e32 v150, v90, v90
	v_fmac_f32_e32 v151, v92, v92
	v_add_f32_e32 v152, v150, v151
	v_add_f32_e32 v161, v161, v152
	v_cvt_pk_f16_f32 v182, v90, v91
	v_cvt_pk_f16_f32 v183, v92, v93
	v_mul_f32_e32 v150, v95, v95
	v_mul_f32_e32 v151, v97, v97
	v_fmac_f32_e32 v150, v94, v94
	v_fmac_f32_e32 v151, v96, v96
	v_add_f32_e32 v152, v150, v151
	v_add_f32_e32 v161, v161, v152
	v_cvt_pk_f16_f32 v184, v94, v95
	v_cvt_pk_f16_f32 v185, v96, v97
	global_store_dwordx2 v145, v[178:179], s[10:11]
	global_store_dwordx2 v145, v[180:181], s[10:11] offset:512
	global_store_dwordx2 v145, v[182:183], s[10:11] offset:1024
	global_store_dwordx2 v145, v[184:185], s[10:11] offset:1536
	v_mul_f32_e32 v150, v99, v99
	v_mul_f32_e32 v151, v101, v101
	v_fmac_f32_e32 v150, v98, v98
	v_fmac_f32_e32 v151, v100, v100
	v_add_f32_e32 v162, v150, v151
	v_cvt_pk_f16_f32 v170, v98, v99
	v_cvt_pk_f16_f32 v171, v100, v101
	v_mul_f32_e32 v150, v103, v103
	v_mul_f32_e32 v151, v105, v105
	v_fmac_f32_e32 v150, v102, v102
	v_fmac_f32_e32 v151, v104, v104
	v_add_f32_e32 v152, v150, v151
	v_add_f32_e32 v162, v162, v152
	v_cvt_pk_f16_f32 v172, v102, v103
	v_cvt_pk_f16_f32 v173, v104, v105
	v_mul_f32_e32 v150, v107, v107
	v_mul_f32_e32 v151, v109, v109
	v_fmac_f32_e32 v150, v106, v106
	v_fmac_f32_e32 v151, v108, v108
; __device__ void p0_xconv(const Args& a) {
;     ...
;         for (int r = 0; r < 4; ++r) {
;             const int row = row0 + r * nwv;
;             if (row < MROWS) {
;                 float ss = 0.f;
; #pragma unroll
;                 for (int i = 0; i < 4; ++i) {
;                     const f32x4 x = v[r][i];
;                     ss += (x[0] * x[0] + x[1] * x[1]) + (x[2] * x[2] + x[3] * x[3]);
;                     f16x4 h; h[0] = (f16)x[0]; h[1] = (f16)x[1]; h[2] = (f16)x[2]; h[3] = (f16)x[3];
;                     *(f16x4*)(XH + (size_t)row * DM + i * 256 + lane * 4) = h;
;                 }
; #pragma unroll
;                 for (int o = 1; o < 64; o <<= 1) ss += __shfl_xor(ss, o);
;                 if (lane < 16) SS[(size_t)row * 16 + lane] = (lane == 0) ? ss : 0.f;
	v_add_f32_e32 v152, v150, v151
	v_add_f32_e32 v162, v162, v152
	v_cvt_pk_f16_f32 v174, v106, v107
	v_cvt_pk_f16_f32 v175, v108, v109
	v_mul_f32_e32 v150, v111, v111
	v_mul_f32_e32 v151, v113, v113
	v_fmac_f32_e32 v150, v110, v110
	v_fmac_f32_e32 v151, v112, v112
	v_add_f32_e32 v152, v150, v151
	v_add_f32_e32 v162, v162, v152
	v_cvt_pk_f16_f32 v176, v110, v111
	v_cvt_pk_f16_f32 v177, v112, v113
	global_store_dwordx2 v146, v[170:171], s[10:11]
	global_store_dwordx2 v146, v[172:173], s[10:11] offset:512
	global_store_dwordx2 v146, v[174:175], s[10:11] offset:1024
	global_store_dwordx2 v146, v[176:177], s[10:11] offset:1536
	v_mul_f32_e32 v150, v115, v115
	v_mul_f32_e32 v151, v117, v117
	v_fmac_f32_e32 v150, v114, v114
	v_fmac_f32_e32 v151, v116, v116
	v_add_f32_e32 v163, v150, v151
	v_cvt_pk_f16_f32 v178, v114, v115
	v_cvt_pk_f16_f32 v179, v116, v117
	v_mul_f32_e32 v150, v119, v119
	v_mul_f32_e32 v151, v121, v121
	v_fmac_f32_e32 v150, v118, v118
	v_fmac_f32_e32 v151, v120, v120
	v_add_f32_e32 v152, v150, v151
	v_add_f32_e32 v163, v163, v152
	v_cvt_pk_f16_f32 v180, v118, v119
	v_cvt_pk_f16_f32 v181, v120, v121
	v_mul_f32_e32 v150, v123, v123
	v_mul_f32_e32 v151, v125, v125
	v_fmac_f32_e32 v150, v122, v122
	v_fmac_f32_e32 v151, v124, v124
	v_add_f32_e32 v152, v150, v151
	v_add_f32_e32 v163, v163, v152
	v_cvt_pk_f16_f32 v182, v122, v123
	v_cvt_pk_f16_f32 v183, v124, v125
	v_mul_f32_e32 v150, v127, v127
	v_mul_f32_e32 v151, v129, v129
	v_fmac_f32_e32 v150, v126, v126
	v_fmac_f32_e32 v151, v128, v128
	v_add_f32_e32 v152, v150, v151
	v_add_f32_e32 v163, v163, v152
	v_cvt_pk_f16_f32 v184, v126, v127
	v_cvt_pk_f16_f32 v185, v128, v129
	global_store_dwordx2 v147, v[178:179], s[10:11]
	global_store_dwordx2 v147, v[180:181], s[10:11] offset:512
	global_store_dwordx2 v147, v[182:183], s[10:11] offset:1024
	global_store_dwordx2 v147, v[184:185], s[10:11] offset:1536
	ds_bpermute_b32 v164, v130, v160
	ds_bpermute_b32 v165, v130, v161
	ds_bpermute_b32 v166, v130, v162
	ds_bpermute_b32 v167, v130, v163
	s_waitcnt lgkmcnt(0)
	v_add_f32_e32 v160, v160, v164
	v_add_f32_e32 v161, v161, v165
	v_add_f32_e32 v162, v162, v166
	v_add_f32_e32 v163, v163, v167
	ds_bpermute_b32 v164, v131, v160
	ds_bpermute_b32 v165, v131, v161
	ds_bpermute_b32 v166, v131, v162
	ds_bpermute_b32 v167, v131, v163
	s_waitcnt lgkmcnt(0)
	v_add_f32_e32 v160, v160, v164
	v_add_f32_e32 v161, v161, v165
	v_add_f32_e32 v162, v162, v166
	v_add_f32_e32 v163, v163, v167
	ds_bpermute_b32 v164, v132, v160
	ds_bpermute_b32 v165, v132, v161
	ds_bpermute_b32 v166, v132, v162
	ds_bpermute_b32 v167, v132, v163
	s_waitcnt lgkmcnt(0)
	v_add_f32_e32 v160, v160, v164
	v_add_f32_e32 v161, v161, v165
	v_add_f32_e32 v162, v162, v166
	v_add_f32_e32 v163, v163, v167
	ds_bpermute_b32 v164, v133, v160
	ds_bpermute_b32 v165, v133, v161
	ds_bpermute_b32 v166, v133, v162
	ds_bpermute_b32 v167, v133, v163
	s_waitcnt lgkmcnt(0)
	v_add_f32_e32 v160, v160, v164
	v_add_f32_e32 v161, v161, v165
	v_add_f32_e32 v162, v162, v166
	v_add_f32_e32 v163, v163, v167
	ds_bpermute_b32 v164, v134, v160
	ds_bpermute_b32 v165, v134, v161
	ds_bpermute_b32 v166, v134, v162
	ds_bpermute_b32 v167, v134, v163
	s_waitcnt lgkmcnt(0)
	v_add_f32_e32 v160, v160, v164
	v_add_f32_e32 v161, v161, v165
	v_add_f32_e32 v162, v162, v166
	v_add_f32_e32 v163, v163, v167
	ds_bpermute_b32 v164, v135, v160
	ds_bpermute_b32 v165, v135, v161
	ds_bpermute_b32 v166, v135, v162
	ds_bpermute_b32 v167, v135, v163
	s_waitcnt lgkmcnt(0)
	v_add_f32_e32 v160, v160, v164
	v_add_f32_e32 v161, v161, v165
	v_add_f32_e32 v162, v162, v166
	v_add_f32_e32 v163, v163, v167
	v_cndmask_b32_e64 v164, 0, v160, s[12:13]
	v_cndmask_b32_e64 v165, 0, v161, s[12:13]
	v_cndmask_b32_e64 v166, 0, v162, s[12:13]
	v_cndmask_b32_e64 v167, 0, v163, s[12:13]
	s_mov_b64 exec, 0xffff
	global_store_dword v186, v164, s[6:7]
	global_store_dword v187, v165, s[6:7]
	global_store_dword v188, v166, s[6:7]
	global_store_dword v189, v167, s[6:7]
	s_mov_b64 exec, -1
	s_waitcnt vmcnt(20)
	s_add_i32 s6, s3, 0xa000
	s_lshl_b32 s7, s6, 11
	s_add_u32 s10, s40, s7
	s_addc_u32 s11, s41, 0
	s_lshl_b32 s7, s6, 6
	s_add_u32 s6, s40, s7
	s_addc_u32 s7, s41, 0
	s_add_u32 s6, s6, 0x1f800000
	s_addc_u32 s7, s7, 0
	v_mul_f32_e32 v150, v3, v3
	v_mul_f32_e32 v151, v5, v5
	v_fmac_f32_e32 v150, v2, v2
	v_fmac_f32_e32 v151, v4, v4
	v_add_f32_e32 v160, v150, v151
	v_cvt_pk_f16_f32 v170, v2, v3
	v_cvt_pk_f16_f32 v171, v4, v5
	v_mul_f32_e32 v150, v7, v7
	v_mul_f32_e32 v151, v9, v9
	v_fmac_f32_e32 v150, v6, v6
	v_fmac_f32_e32 v151, v8, v8
	v_add_f32_e32 v152, v150, v151
	v_add_f32_e32 v160, v160, v152
	v_cvt_pk_f16_f32 v172, v6, v7
	v_cvt_pk_f16_f32 v173, v8, v9
	v_mul_f32_e32 v150, v11, v11
	v_mul_f32_e32 v151, v13, v13
	v_fmac_f32_e32 v150, v10, v10
	v_fmac_f32_e32 v151, v12, v12
	v_add_f32_e32 v152, v150, v151
	v_add_f32_e32 v160, v160, v152
	v_cvt_pk_f16_f32 v174, v10, v11
	v_cvt_pk_f16_f32 v175, v12, v13
	v_mul_f32_e32 v150, v15, v15
	v_mul_f32_e32 v151, v17, v17
	v_fmac_f32_e32 v150, v14, v14
	v_fmac_f32_e32 v151, v16, v16
	v_add_f32_e32 v152, v150, v151
	v_add_f32_e32 v160, v160, v152
	v_cvt_pk_f16_f32 v176, v14, v15
	v_cvt_pk_f16_f32 v177, v16, v17
	global_store_dwordx2 v144, v[170:171], s[10:11]
	global_store_dwordx2 v144, v[172:173], s[10:11] offset:512
	global_store_dwordx2 v144, v[174:175], s[10:11] offset:1024
	global_store_dwordx2 v144, v[176:177], s[10:11] offset:1536
	v_mul_f32_e32 v150, v19, v19
	v_mul_f32_e32 v151, v21, v21
	v_fmac_f32_e32 v150, v18, v18
	v_fmac_f32_e32 v151, v20, v20
	v_add_f32_e32 v161, v150, v151
	v_cvt_pk_f16_f32 v178, v18, v19
	v_cvt_pk_f16_f32 v179, v20, v21
	v_mul_f32_e32 v150, v23, v23
; __device__ void p0_xconv(const Args& a) {
;     ...
;         for (int r = 0; r < 4; ++r) {
;             const int row = row0 + r * nwv;
;             if (row < MROWS) {
;                 float ss = 0.f;
; #pragma unroll
;                 for (int i = 0; i < 4; ++i) {
;                     const f32x4 x = v[r][i];
;                     ss += (x[0] * x[0] + x[1] * x[1]) + (x[2] * x[2] + x[3] * x[3]);
;                     f16x4 h; h[0] = (f16)x[0]; h[1] = (f16)x[1]; h[2] = (f16)x[2]; h[3] = (f16)x[3];
;                     *(f16x4*)(XH + (size_t)row * DM + i * 256 + lane * 4) = h;
;                 }
; #pragma unroll
;                 for (int o = 1; o < 64; o <<= 1) ss += __shfl_xor(ss, o);
;                 if (lane < 16) SS[(size_t)row * 16 + lane] = (lane == 0) ? ss : 0.f;
	v_mul_f32_e32 v151, v25, v25
	v_fmac_f32_e32 v150, v22, v22
	v_fmac_f32_e32 v151, v24, v24
	v_add_f32_e32 v152, v150, v151
	v_add_f32_e32 v161, v161, v152
	v_cvt_pk_f16_f32 v180, v22, v23
	v_cvt_pk_f16_f32 v181, v24, v25
	v_mul_f32_e32 v150, v27, v27
	v_mul_f32_e32 v151, v29, v29
	v_fmac_f32_e32 v150, v26, v26
	v_fmac_f32_e32 v151, v28, v28
	v_add_f32_e32 v152, v150, v151
	v_add_f32_e32 v161, v161, v152
	v_cvt_pk_f16_f32 v182, v26, v27
	v_cvt_pk_f16_f32 v183, v28, v29
	v_mul_f32_e32 v150, v31, v31
	v_mul_f32_e32 v151, v33, v33
	v_fmac_f32_e32 v150, v30, v30
	v_fmac_f32_e32 v151, v32, v32
	v_add_f32_e32 v152, v150, v151
	v_add_f32_e32 v161, v161, v152
	v_cvt_pk_f16_f32 v184, v30, v31
	v_cvt_pk_f16_f32 v185, v32, v33
	global_store_dwordx2 v145, v[178:179], s[10:11]
	global_store_dwordx2 v145, v[180:181], s[10:11] offset:512
	global_store_dwordx2 v145, v[182:183], s[10:11] offset:1024
	global_store_dwordx2 v145, v[184:185], s[10:11] offset:1536
	v_mul_f32_e32 v150, v35, v35
	v_mul_f32_e32 v151, v37, v37
	v_fmac_f32_e32 v150, v34, v34
	v_fmac_f32_e32 v151, v36, v36
	v_add_f32_e32 v162, v150, v151
	v_cvt_pk_f16_f32 v170, v34, v35
	v_cvt_pk_f16_f32 v171, v36, v37
	v_mul_f32_e32 v150, v39, v39
	v_mul_f32_e32 v151, v41, v41
	v_fmac_f32_e32 v150, v38, v38
	v_fmac_f32_e32 v151, v40, v40
	v_add_f32_e32 v152, v150, v151
	v_add_f32_e32 v162, v162, v152
	v_cvt_pk_f16_f32 v172, v38, v39
	v_cvt_pk_f16_f32 v173, v40, v41
	v_mul_f32_e32 v150, v43, v43
	v_mul_f32_e32 v151, v45, v45
	v_fmac_f32_e32 v150, v42, v42
	v_fmac_f32_e32 v151, v44, v44
	v_add_f32_e32 v152, v150, v151
	v_add_f32_e32 v162, v162, v152
	v_cvt_pk_f16_f32 v174, v42, v43
	v_cvt_pk_f16_f32 v175, v44, v45
	v_mul_f32_e32 v150, v47, v47
	v_mul_f32_e32 v151, v49, v49
	v_fmac_f32_e32 v150, v46, v46
	v_fmac_f32_e32 v151, v48, v48
	v_add_f32_e32 v152, v150, v151
	v_add_f32_e32 v162, v162, v152
	v_cvt_pk_f16_f32 v176, v46, v47
	v_cvt_pk_f16_f32 v177, v48, v49
	global_store_dwordx2 v146, v[170:171], s[10:11]
	global_store_dwordx2 v146, v[172:173], s[10:11] offset:512
	global_store_dwordx2 v146, v[174:175], s[10:11] offset:1024
	global_store_dwordx2 v146, v[176:177], s[10:11] offset:1536
	v_mul_f32_e32 v150, v51, v51
	v_mul_f32_e32 v151, v53, v53
	v_fmac_f32_e32 v150, v50, v50
	v_fmac_f32_e32 v151, v52, v52
	v_add_f32_e32 v163, v150, v151
	v_cvt_pk_f16_f32 v178, v50, v51
	v_cvt_pk_f16_f32 v179, v52, v53
	v_mul_f32_e32 v150, v55, v55
	v_mul_f32_e32 v151, v57, v57
	v_fmac_f32_e32 v150, v54, v54
	v_fmac_f32_e32 v151, v56, v56
	v_add_f32_e32 v152, v150, v151
	v_add_f32_e32 v163, v163, v152
	v_cvt_pk_f16_f32 v180, v54, v55
	v_cvt_pk_f16_f32 v181, v56, v57
	v_mul_f32_e32 v150, v59, v59
	v_mul_f32_e32 v151, v61, v61
	v_fmac_f32_e32 v150, v58, v58
	v_fmac_f32_e32 v151, v60, v60
	v_add_f32_e32 v152, v150, v151
	v_add_f32_e32 v163, v163, v152
	v_cvt_pk_f16_f32 v182, v58, v59
	v_cvt_pk_f16_f32 v183, v60, v61
	v_mul_f32_e32 v150, v63, v63
	v_mul_f32_e32 v151, v65, v65
	v_fmac_f32_e32 v150, v62, v62
	v_fmac_f32_e32 v151, v64, v64
	v_add_f32_e32 v152, v150, v151
	v_add_f32_e32 v163, v163, v152
	v_cvt_pk_f16_f32 v184, v62, v63
	v_cvt_pk_f16_f32 v185, v64, v65
	global_store_dwordx2 v147, v[178:179], s[10:11]
	global_store_dwordx2 v147, v[180:181], s[10:11] offset:512
	global_store_dwordx2 v147, v[182:183], s[10:11] offset:1024
	global_store_dwordx2 v147, v[184:185], s[10:11] offset:1536
	ds_bpermute_b32 v164, v130, v160
	ds_bpermute_b32 v165, v130, v161
	ds_bpermute_b32 v166, v130, v162
	ds_bpermute_b32 v167, v130, v163
	s_waitcnt lgkmcnt(0)
	v_add_f32_e32 v160, v160, v164
	v_add_f32_e32 v161, v161, v165
	v_add_f32_e32 v162, v162, v166
	v_add_f32_e32 v163, v163, v167
	ds_bpermute_b32 v164, v131, v160
	ds_bpermute_b32 v165, v131, v161
	ds_bpermute_b32 v166, v131, v162
	ds_bpermute_b32 v167, v131, v163
	s_waitcnt lgkmcnt(0)
	v_add_f32_e32 v160, v160, v164
	v_add_f32_e32 v161, v161, v165
	v_add_f32_e32 v162, v162, v166
	v_add_f32_e32 v163, v163, v167
	ds_bpermute_b32 v164, v132, v160
	ds_bpermute_b32 v165, v132, v161
	ds_bpermute_b32 v166, v132, v162
	ds_bpermute_b32 v167, v132, v163
	s_waitcnt lgkmcnt(0)
	v_add_f32_e32 v160, v160, v164
	v_add_f32_e32 v161, v161, v165
	v_add_f32_e32 v162, v162, v166
	v_add_f32_e32 v163, v163, v167
	ds_bpermute_b32 v164, v133, v160
	ds_bpermute_b32 v165, v133, v161
	ds_bpermute_b32 v166, v133, v162
	ds_bpermute_b32 v167, v133, v163
	s_waitcnt lgkmcnt(0)
	v_add_f32_e32 v160, v160, v164
	v_add_f32_e32 v161, v161, v165
	v_add_f32_e32 v162, v162, v166
	v_add_f32_e32 v163, v163, v167
	ds_bpermute_b32 v164, v134, v160
	ds_bpermute_b32 v165, v134, v161
	ds_bpermute_b32 v166, v134, v162
	ds_bpermute_b32 v167, v134, v163
	s_waitcnt lgkmcnt(0)
	v_add_f32_e32 v160, v160, v164
	v_add_f32_e32 v161, v161, v165
	v_add_f32_e32 v162, v162, v166
	v_add_f32_e32 v163, v163, v167
	ds_bpermute_b32 v164, v135, v160
	ds_bpermute_b32 v165, v135, v161
	ds_bpermute_b32 v166, v135, v162
	ds_bpermute_b32 v167, v135, v163
	s_waitcnt lgkmcnt(0)
	v_add_f32_e32 v160, v160, v164
	v_add_f32_e32 v161, v161, v165
	v_add_f32_e32 v162, v162, v166
	v_add_f32_e32 v163, v163, v167
	v_cndmask_b32_e64 v164, 0, v160, s[12:13]
	v_cndmask_b32_e64 v165, 0, v161, s[12:13]
	v_cndmask_b32_e64 v166, 0, v162, s[12:13]
	v_cndmask_b32_e64 v167, 0, v163, s[12:13]
	s_mov_b64 exec, 0xffff
	global_store_dword v186, v164, s[6:7]
	global_store_dword v187, v165, s[6:7]
	global_store_dword v188, v166, s[6:7]
	global_store_dword v189, v167, s[6:7]
	s_mov_b64 exec, -1
	s_waitcnt vmcnt(0)
; #define LAS __attribute__((address_space(3)))
; __device__ void p_weights_prod(const Args& a, LAS unsigned char* lds) {
;     ...
;         f32x4 acc[4];
; #pragma unroll
;         for (int r2 = 0; r2 < 4; ++r2) acc[r2] = (f32x4){0.f, 0.f, 0.f, 0.f};
; #pragma unroll 2
;         for (int c0 = 0; c0 < 128; c0 += 4) {
;             f32x4 w4[4], m4[4];
; #pragma unroll
;             for (int r2 = 0; r2 < 4; ++r2) w4[r2] = *(const LAS f32x4*)(wt + (4 * rq + r2) * 128 + c0);
; #pragma unroll
;             for (int cc = 0; cc < 4; ++cc) m4[cc] = *(const LAS f32x4*)(mmt + (c0 + cc) * 256 + lc0);
; #pragma unroll
;             for (int r2 = 0; r2 < 4; ++r2)
; #pragma unroll
;                 for (int cc = 0; cc < 4; ++cc) acc[r2] += m4[cc] * w4[r2][cc];
;         }
	v_mov_b32_e32 v8, v0
	v_lshlrev_b32_e32 v10, 4, v8
	s_load_dword s9, s[0:1], 0x60
	s_add_u32 s6, s40, 0x1fb00000
	v_lshlrev_b32_e32 v1, 1, v8
	v_and_b32_e32 v2, 0x90, v10
	s_movk_i32 s3, 0x6c
	v_lshlrev_b32_e32 v3, 3, v8
	v_ashrrev_i32_e32 v9, 31, v8
	s_addc_u32 s7, s41, 0
	v_and_or_b32 v2, v1, s3, v2
	v_ashrrev_i32_e32 v11, 6, v8
	v_ashrrev_i32_e32 v1, 4, v8
	v_and_b32_e32 v4, 0x78, v3
	v_lshl_add_u64 v[6:7], v[8:9], 4, s[40:41]
	s_mov_b64 s[4:5], 0x20a00000
	v_and_b32_e32 v8, 63, v8
	v_lshl_add_u64 v[6:7], v[6:7], 0, s[4:5]
	v_lshlrev_b32_e32 v3, 9, v1
	v_lshlrev_b32_e32 v9, 2, v4
	v_add_u32_e32 v24, 0, v10
	s_add_u32 s4, s0, 0x60
	v_lshl_add_u32 v8, v8, 4, 0
	v_mov_b32_e32 v5, 0
	s_mov_b32 s11, 0
	v_add3_u32 v3, 0, v3, v9
	s_movk_i32 s3, 0x4000
	v_add_u32_e32 v25, 0x4000, v24
	v_lshl_add_u32 v26, v11, 11, 0
	v_lshlrev_b32_e32 v27, 2, v11
	s_addc_u32 s5, s1, 0
	s_mov_b32 s14, 0x14000
	v_add_u32_e32 v28, 0x14000, v24
	s_mov_b32 s15, 0x16000
	v_add_u32_e32 v29, 0x16000, v24
	s_mov_b32 s33, 0x18000
	v_add_u32_e32 v30, 0x18000, v24
	s_mov_b32 s34, 0x1a000
	v_add_u32_e32 v31, 0x1a000, v24
	s_mov_b32 s35, 0x1c000
	v_add_u32_e32 v32, 0x1c000, v24
	s_mov_b32 s36, 0x1e000
	v_add_u32_e32 v33, 0x1e000, v24
	v_add_u32_e32 v34, 0x20000, v24
	v_add_u32_e32 v35, 0x22000, v24
	v_add_u32_e32 v36, 0x4000, v8
	s_movk_i32 s37, 0x2400
	s_movk_i32 s44, 0x2000
	s_movk_i32 s45, 0x6000
	s_mov_b32 s46, 0x8000
	s_mov_b32 s47, 0xa000
	s_mov_b32 s48, 0xc000
	s_mov_b32 s49, 0xe000
	s_mov_b32 s50, 0x10000
	s_mov_b32 s51, 0x12000
	v_lshlrev_b32_e32 v4, 2, v4
	s_mov_b64 s[12:13], 0x1400
	s_movk_i32 s52, 0x1000
	s_mov_b32 s53, s2
	s_ashr_i32 s55, s53, 7
	s_bfe_u32 s54, s53, 0x20005
	s_mul_i32 s56, s55, 0x900000
	s_mul_hi_i32 s10, s55, 0x900000
	s_add_u32 s58, s22, s56
	s_addc_u32 s59, s23, s10
	s_lshl_b32 s10, s53, 5
	s_and_b32 s56, s10, 0x3e0
	v_add_u32_e32 v10, s56, v1
	v_mov_b64_e32 v[8:9], s[58:59]
	v_mad_i64_i32 v[8:9], s[58:59], v10, s37, v[8:9]
	s_lshl_b32 s10, s54, 9
	v_lshl_add_u64 v[8:9], v[8:9], 0, s[10:11]
	s_lshl_b32 s10, s55, 2
	s_or_b32 s58, s10, s54
	v_lshl_add_u64 v[8:9], v[8:9], 0, v[4:5]
	s_ashr_i32 s59, s58, 31
	v_add_co_u32_e32 v10, vcc, s52, v8
	s_lshl_b64 s[58:59], s[58:59], 17
	s_nop 0
	v_addc_co_u32_e32 v11, vcc, 0, v9, vcc
	v_lshl_add_u64 v[86:87], v[6:7], 0, s[58:59]
	v_add_co_u32_e32 v20, vcc, s44, v86
	v_lshl_add_u64 v[12:13], v[8:9], 0, s[12:13]
	s_nop 0
	v_addc_co_u32_e32 v21, vcc, 0, v87, vcc
	v_add_co_u32_e32 v38, vcc, s3, v86
	s_waitcnt lgkmcnt(0)
	s_nop 0
	v_addc_co_u32_e32 v39, vcc, 0, v87, vcc
	v_add_co_u32_e32 v42, vcc, s45, v86
	s_nop 0
	v_addc_co_u32_e32 v43, vcc, 0, v87, vcc
	v_add_co_u32_e32 v46, vcc, s46, v86
	s_nop 1
	v_addc_co_u32_e32 v47, vcc, 0, v87, vcc
	v_add_co_u32_e32 v50, vcc, s47, v86
	s_nop 0
	v_addc_co_u32_e32 v51, vcc, 0, v87, vcc
	v_add_co_u32_e32 v54, vcc, s48, v86
	s_nop 0
	v_addc_co_u32_e32 v55, vcc, 0, v87, vcc
	v_add_co_u32_e32 v58, vcc, s49, v86
	s_nop 0
	v_addc_co_u32_e32 v59, vcc, 0, v87, vcc
	v_add_co_u32_e32 v62, vcc, s50, v86
	s_nop 0
	v_addc_co_u32_e32 v63, vcc, 0, v87, vcc
	v_add_co_u32_e32 v66, vcc, s51, v86
	s_mov_b32 s10, -4
	s_nop 0
	v_addc_co_u32_e32 v67, vcc, 0, v87, vcc
	v_add_co_u32_e32 v70, vcc, s14, v86
	v_mov_b32_e32 v37, v26
	s_nop 0
	v_addc_co_u32_e32 v71, vcc, 0, v87, vcc
	v_add_co_u32_e32 v74, vcc, s15, v86
	s_nop 1
	v_addc_co_u32_e32 v75, vcc, 0, v87, vcc
	v_add_co_u32_e32 v78, vcc, s33, v86
	s_nop 0
	s_nop 0
	s_nop 0
	s_nop 0
	s_nop 0
	v_addc_co_u32_e32 v79, vcc, 0, v87, vcc
	v_add_co_u32_e32 v82, vcc, s34, v86
	s_nop 1
	v_addc_co_u32_e32 v83, vcc, 0, v87, vcc
	v_add_co_u32_e32 v88, vcc, s35, v86
	s_nop 0
	v_addc_co_u32_e32 v89, vcc, 0, v87, vcc
	v_add_co_u32_e32 v90, vcc, s36, v86
	s_nop 1
	v_addc_co_u32_e32 v91, vcc, 0, v87, vcc
	s_nop 0
	s_waitcnt vmcnt(0)
	v_mov_b32_e32 v38, v36
	v_mov_b32_e32 v10, 0
	v_mov_b32_e32 v11, v5
	v_mov_b32_e32 v8, 0
	v_mov_b32_e32 v9, v5
	v_mov_b32_e32 v22, 0
	v_mov_b32_e32 v23, v5
	v_mov_b32_e32 v20, 0
	v_mov_b32_e32 v21, v5
	v_mov_b32_e32 v14, 0
	v_mov_b32_e32 v15, v5
	v_mov_b32_e32 v12, 0
	v_mov_b32_e32 v13, v5
	v_mov_b32_e32 v18, 0
	v_mov_b32_e32 v19, v5
	v_mov_b32_e32 v16, 0
	v_mov_b32_e32 v17, v5
.Lpw_kb:
	ds_read_b128 v[40:43], v38
	ds_read_b128 v[44:47], v38 offset:1024
	ds_read_b128 v[48:51], v38 offset:2048
	ds_read_b128 v[52:55], v38 offset:3072
	ds_read_b128 v[56:59], v37
	ds_read_b128 v[60:63], v37 offset:16
	ds_read_b128 v[64:67], v37 offset:512
	ds_read_b128 v[68:71], v37 offset:528
	ds_read_b128 v[72:75], v37 offset:1024
	ds_read_b128 v[76:79], v37 offset:1040
	ds_read_b128 v[80:83], v37 offset:1536
	ds_read_b128 v[84:87], v37 offset:1552
	ds_read_b128 v[88:91], v38 offset:4096
	ds_read_b128 v[92:95], v38 offset:5120
	ds_read_b128 v[96:99], v38 offset:6144
	ds_read_b128 v[100:103], v38 offset:7168
	s_waitcnt lgkmcnt(11)
	v_pk_fma_f32 v[8:9], v[56:57], v[42:43], v[8:9] op_sel_hi:[0,1,1]
	v_pk_fma_f32 v[10:11], v[56:57], v[40:41], v[10:11] op_sel_hi:[0,1,1]
	s_waitcnt lgkmcnt(9)
	v_pk_fma_f32 v[20:21], v[64:65], v[42:43], v[20:21] op_sel_hi:[0,1,1]
	v_pk_fma_f32 v[22:23], v[64:65], v[40:41], v[22:23] op_sel_hi:[0,1,1]
	s_waitcnt lgkmcnt(7)
	v_pk_fma_f32 v[12:13], v[72:73], v[42:43], v[12:13] op_sel_hi:[0,1,1]
	v_pk_fma_f32 v[14:15], v[72:73], v[40:41], v[14:15] op_sel_hi:[0,1,1]
	s_waitcnt lgkmcnt(5)
; #define LAS __attribute__((address_space(3)))
; __device__ void p_weights_prod(const Args& a, LAS unsigned char* lds) {
;     ...
;         for (int c0 = 0; c0 < 128; c0 += 4) {
;             f32x4 w4[4], m4[4];
; #pragma unroll
;             for (int r2 = 0; r2 < 4; ++r2) w4[r2] = *(const LAS f32x4*)(wt + (4 * rq + r2) * 128 + c0);
; #pragma unroll
;             for (int cc = 0; cc < 4; ++cc) m4[cc] = *(const LAS f32x4*)(mmt + (c0 + cc) * 256 + lc0);
; #pragma unroll
;             for (int r2 = 0; r2 < 4; ++r2)
; #pragma unroll
;                 for (int cc = 0; cc < 4; ++cc) acc[r2] += m4[cc] * w4[r2][cc];
;         }
;         const int k0 = kblk * 32 + 4 * rq;
;         const f32x4 gn = *(const f32x4*)(a.norm_gain + l * DM + k0);
; #pragma unroll
;         for (int j = 0; j < 4; ++j) {
;             f16x4 o;
; #pragma unroll
;             for (int r2 = 0; r2 < 4; ++r2) o[r2] = (f16)(acc[r2][j] * gn[r2]);
;             *(f16x4*)(W1T + ((size_t)l * N1 + pn * 256 + rho0 + j) * 1024 + k0) = o;
;         }
	v_pk_fma_f32 v[16:17], v[42:43], v[80:81], v[16:17] op_sel_hi:[1,0,1]
	v_pk_fma_f32 v[18:19], v[40:41], v[80:81], v[18:19] op_sel_hi:[1,0,1]
	v_pk_fma_f32 v[8:9], v[56:57], v[46:47], v[8:9] op_sel:[1,0,0]
	v_pk_fma_f32 v[10:11], v[56:57], v[44:45], v[10:11] op_sel:[1,0,0]
	v_pk_fma_f32 v[20:21], v[64:65], v[46:47], v[20:21] op_sel:[1,0,0]
	v_pk_fma_f32 v[22:23], v[64:65], v[44:45], v[22:23] op_sel:[1,0,0]
	v_pk_fma_f32 v[12:13], v[72:73], v[46:47], v[12:13] op_sel:[1,0,0]
	v_pk_fma_f32 v[14:15], v[72:73], v[44:45], v[14:15] op_sel:[1,0,0]
	v_pk_fma_f32 v[16:17], v[80:81], v[46:47], v[16:17] op_sel:[1,0,0]
	v_pk_fma_f32 v[18:19], v[80:81], v[44:45], v[18:19] op_sel:[1,0,0]
	v_mov_b32_e32 v40, v59
	v_mov_b32_e32 v42, v67
	v_mov_b32_e32 v104, v75
	v_mov_b32_e32 v106, v83
	v_pk_fma_f32 v[10:11], v[58:59], v[48:49], v[10:11] op_sel_hi:[0,1,1]
	v_pk_fma_f32 v[8:9], v[58:59], v[50:51], v[8:9] op_sel_hi:[0,1,1]
	v_pk_fma_f32 v[22:23], v[66:67], v[48:49], v[22:23] op_sel_hi:[0,1,1]
	v_pk_fma_f32 v[20:21], v[66:67], v[50:51], v[20:21] op_sel_hi:[0,1,1]
	v_pk_fma_f32 v[14:15], v[74:75], v[48:49], v[14:15] op_sel_hi:[0,1,1]
	v_pk_fma_f32 v[12:13], v[74:75], v[50:51], v[12:13] op_sel_hi:[0,1,1]
	v_pk_fma_f32 v[18:19], v[82:83], v[48:49], v[18:19] op_sel_hi:[0,1,1]
	v_pk_fma_f32 v[16:17], v[82:83], v[50:51], v[16:17] op_sel_hi:[0,1,1]
	v_pk_fma_f32 v[8:9], v[40:41], v[54:55], v[8:9] op_sel_hi:[0,1,1]
	v_pk_fma_f32 v[10:11], v[40:41], v[52:53], v[10:11] op_sel_hi:[0,1,1]
	v_pk_fma_f32 v[20:21], v[42:43], v[54:55], v[20:21] op_sel_hi:[0,1,1]
	v_pk_fma_f32 v[22:23], v[42:43], v[52:53], v[22:23] op_sel_hi:[0,1,1]
	v_pk_fma_f32 v[12:13], v[104:105], v[54:55], v[12:13] op_sel_hi:[0,1,1]
	v_pk_fma_f32 v[14:15], v[104:105], v[52:53], v[14:15] op_sel_hi:[0,1,1]
	v_pk_fma_f32 v[16:17], v[106:107], v[54:55], v[16:17] op_sel_hi:[0,1,1]
	v_pk_fma_f32 v[18:19], v[106:107], v[52:53], v[18:19] op_sel_hi:[0,1,1]
	s_waitcnt lgkmcnt(3)
	v_pk_fma_f32 v[10:11], v[60:61], v[88:89], v[10:11] op_sel_hi:[0,1,1]
	v_pk_fma_f32 v[8:9], v[60:61], v[90:91], v[8:9] op_sel_hi:[0,1,1]
	v_pk_fma_f32 v[22:23], v[68:69], v[88:89], v[22:23] op_sel_hi:[0,1,1]
	v_pk_fma_f32 v[20:21], v[68:69], v[90:91], v[20:21] op_sel_hi:[0,1,1]
	v_pk_fma_f32 v[14:15], v[76:77], v[88:89], v[14:15] op_sel_hi:[0,1,1]
	v_pk_fma_f32 v[12:13], v[76:77], v[90:91], v[12:13] op_sel_hi:[0,1,1]
	v_pk_fma_f32 v[18:19], v[88:89], v[84:85], v[18:19] op_sel_hi:[1,0,1]
	v_pk_fma_f32 v[16:17], v[90:91], v[84:85], v[16:17] op_sel_hi:[1,0,1]
	s_waitcnt lgkmcnt(2)
	v_pk_fma_f32 v[8:9], v[60:61], v[94:95], v[8:9] op_sel:[1,0,0]
	v_pk_fma_f32 v[10:11], v[60:61], v[92:93], v[10:11] op_sel:[1,0,0]
	v_pk_fma_f32 v[20:21], v[68:69], v[94:95], v[20:21] op_sel:[1,0,0]
	v_pk_fma_f32 v[22:23], v[68:69], v[92:93], v[22:23] op_sel:[1,0,0]
	v_pk_fma_f32 v[12:13], v[76:77], v[94:95], v[12:13] op_sel:[1,0,0]
	v_pk_fma_f32 v[14:15], v[76:77], v[92:93], v[14:15] op_sel:[1,0,0]
	v_pk_fma_f32 v[16:17], v[84:85], v[94:95], v[16:17] op_sel:[1,0,0]
	v_pk_fma_f32 v[18:19], v[84:85], v[92:93], v[18:19] op_sel:[1,0,0]
	s_add_i32 s10, s10, 8
	v_mov_b32_e32 v108, v63
	v_mov_b32_e32 v110, v71
	v_mov_b32_e32 v112, v79
	v_mov_b32_e32 v114, v87
	s_waitcnt lgkmcnt(1)
	v_pk_fma_f32 v[10:11], v[62:63], v[96:97], v[10:11] op_sel_hi:[0,1,1]
	v_pk_fma_f32 v[8:9], v[62:63], v[98:99], v[8:9] op_sel_hi:[0,1,1]
	v_pk_fma_f32 v[22:23], v[70:71], v[96:97], v[22:23] op_sel_hi:[0,1,1]
	v_pk_fma_f32 v[20:21], v[70:71], v[98:99], v[20:21] op_sel_hi:[0,1,1]
	v_pk_fma_f32 v[14:15], v[78:79], v[96:97], v[14:15] op_sel_hi:[0,1,1]
	v_pk_fma_f32 v[12:13], v[78:79], v[98:99], v[12:13] op_sel_hi:[0,1,1]
	v_pk_fma_f32 v[18:19], v[86:87], v[96:97], v[18:19] op_sel_hi:[0,1,1]
	v_pk_fma_f32 v[16:17], v[86:87], v[98:99], v[16:17] op_sel_hi:[0,1,1]
	v_add_u32_e32 v38, 0x2000, v38
	v_add_u32_e32 v37, 32, v37
	s_cmpk_gt_u32 s10, 0x7b
	s_waitcnt lgkmcnt(0)
	v_pk_fma_f32 v[8:9], v[108:109], v[102:103], v[8:9] op_sel_hi:[0,1,1]
	v_pk_fma_f32 v[10:11], v[108:109], v[100:101], v[10:11] op_sel_hi:[0,1,1]
	v_pk_fma_f32 v[20:21], v[110:111], v[102:103], v[20:21] op_sel_hi:[0,1,1]
	v_pk_fma_f32 v[22:23], v[110:111], v[100:101], v[22:23] op_sel_hi:[0,1,1]
	v_pk_fma_f32 v[12:13], v[112:113], v[102:103], v[12:13] op_sel_hi:[0,1,1]
	v_pk_fma_f32 v[14:15], v[112:113], v[100:101], v[14:15] op_sel_hi:[0,1,1]
	v_pk_fma_f32 v[16:17], v[114:115], v[102:103], v[16:17] op_sel_hi:[0,1,1]
	v_pk_fma_f32 v[18:19], v[114:115], v[100:101], v[18:19] op_sel_hi:[0,1,1]
	s_cbranch_scc0 .Lpw_kb
	v_add_u32_e32 v42, s56, v27
	s_lshl_b32 s56, s55, 10
	s_ashr_i32 s57, s56, 31
	s_lshl_b64 s[56:57], s[56:57], 2
	s_add_u32 s56, s20, s56
	s_addc_u32 s57, s21, s57
	v_ashrrev_i32_e32 v43, 31, v42
	v_lshl_add_u64 v[38:39], v[42:43], 2, s[56:57]
	global_load_dwordx4 v[38:41], v[38:39], off
	s_lshl_b32 s54, s54, 8
	s_mul_hi_i32 s10, s55, 0xb00
	s_mulk_i32 s55, 0xb00
	s_addk_i32 s54, 0x700
	s_add_u32 s54, s55, s54
	s_addc_u32 s10, s10, 0
	v_mov_b32_e32 v44, v22
	v_mov_b32_e32 v45, v14
	v_mov_b32_e32 v14, v23
	v_mov_b32_e32 v22, v20
	v_mov_b32_e32 v23, v12
	v_mov_b32_e32 v12, v21
	v_lshl_add_u64 v[20:21], v[42:43], 1, s[6:7]
	v_or_b32_e32 v42, s54, v2
	v_mov_b32_e32 v43, s10
	v_lshlrev_b64 v[42:43], 11, v[42:43]
	v_lshl_add_u64 v[46:47], v[20:21], 0, v[42:43]
	v_or_b32_e32 v48, 0x800, v42
	v_mov_b32_e32 v49, v43
	v_or_b32_e32 v50, 0x1000, v42
	v_mov_b32_e32 v51, v43
	v_or_b32_e32 v42, 0x1800, v42
	v_lshl_add_u64 v[48:49], v[20:21], 0, v[48:49]
	v_lshl_add_u64 v[50:51], v[20:21], 0, v[50:51]
	v_lshl_add_u64 v[20:21], v[20:21], 0, v[42:43]
	s_add_i32 s53, s53, s9
	s_cmpk_gt_i32 s53, 0xff
	s_waitcnt vmcnt(0)
	v_mov_b32_e32 v42, v39
	v_mov_b32_e32 v43, v40
	v_fma_mixlo_f16 v37, v10, v38, 0
	v_fma_mixlo_f16 v39, v11, v38, 0
	v_fma_mixlo_f16 v40, v8, v38, 0
	v_fma_mixlo_f16 v38, v9, v38, 0
	v_pk_mul_f32 v[8:9], v[44:45], v[42:43]
	v_fma_mixlo_f16 v18, v18, v41, 0
	v_pk_mul_f32 v[10:11], v[14:15], v[42:43]
	v_pk_mul_f32 v[14:15], v[22:23], v[42:43]
	v_pk_mul_f32 v[12:13], v[12:13], v[42:43]
	v_cvt_pk_f16_f32 v9, v8, v9
	v_fma_mixlo_f16 v19, v19, v41, 0
	v_fma_mixlo_f16 v16, v16, v41, 0
	v_fma_mixlo_f16 v17, v17, v41, 0
	v_cvt_pk_f16_f32 v11, v10, v11
	v_cvt_pk_f16_f32 v14, v14, v15
	v_cvt_pk_f16_f32 v15, v12, v13
	v_pack_b32_f16 v8, v37, v9
	v_alignbit_b32 v9, v18, v9, 16
	v_pack_b32_f16 v10, v39, v11
	v_alignbit_b32 v11, v19, v11, 16
	v_pack_b32_f16 v12, v40, v14
	v_alignbit_b32 v13, v16, v14, 16
	v_pack_b32_f16 v14, v38, v15
	v_alignbit_b32 v15, v17, v15, 16
	global_store_dwordx2 v[46:47], v[8:9], off
	global_store_dwordx2 v[48:49], v[10:11], off
	global_store_dwordx2 v[50:51], v[12:13], off
	global_store_dwordx2 v[20:21], v[14:15], off
	s_barrier
	s_branch .LBB0_112
